# p4 de-waterfall: second half of the unit's q/k rows and the V rows are requested earlier (with the first request / between the rotary blocks) instead of after full drains; on top of p4_loghoist
# baseline (speedup 1.0000x reference)
; __device__ __forceinline__ u32x4 ws_load16(const WsRef& w, unsigned byte_off) { return __builtin_bit_cast(u32x4, __builtin_amdgcn_raw_buffer_load_b128(w.r, byte_off, 0, 0)); }
; __device__ __forceinline__ void ret_unit(LAS unsigned char* lds, int u, const bf16* PROJ, const int* pos, const float* dec_f, const float* dec_b, const bf16* ST,
;                                          const float* gn_w, const float* gn_b, bf16* MIX, int tid, const WsRef& wsr) {
;     ...
;     u32x4 rq1[2], rq2[2], rk1[2], rk2[2], rv[4]; float rp[2];
; #pragma unroll
;     for (int ii = 0; ii < 2; ++ii) { const int it = tid + 512 * ii, dc = it & 7, j = it >> 3; const unsigned qo = (unsigned)WS_PROJ + (unsigned)(((unsigned)(row0 + j) * INC + h * 128 + dc * 8) * 2u);
;         rq1[ii] = ws_load16(wsr, qo); rq2[ii] = ws_load16(wsr, qo + 128u); rk1[ii] = ws_load16(wsr, qo + 1024u); rk2[ii] = ws_load16(wsr, qo + 1152u); rp[ii] = (float)pos[row0 + j]; }
.LBB0_438:
	s_ashr_i32 s0, s73, 6
	s_and_b32 s80, s0, 3
	s_lshl_b32 s1, s80, 2
	v_mov_b32_e32 v86, s1
	global_load_dword v68, v86, s[18:19]
	global_load_dword v87, v86, s[20:21]
	s_and_b32 s82, s73, 63
	s_ashr_i32 s4, s73, 8
	s_ashr_i32 s5, s4, 31
	s_lshl_b32 s81, s82, 7
	s_ashr_i32 s1, s0, 31
	s_lshl_b64 s[0:1], s[0:1], 21
	s_add_u32 s0, s54, s0
	s_addc_u32 s1, s55, s1
	s_mov_b32 s88, s84
	s_movk_i32 s8, 0x2000
	s_lshl_b32 s68, s82, 15
	s_add_u32 s0, s0, s68
	s_addc_u32 s1, s1, 0
	s_add_u32 s82, s0, 0x1000000
	v_lshl_add_u64 v[2:3], s[0:1], 0, v[96:97]
	s_addc_u32 s83, s1, 0
	v_add_co_u32_e64 v8, s[68:69], s8, v2
	v_lshl_add_u64 v[28:29], s[82:83], 0, v[96:97]
	s_nop 0
	v_addc_co_u32_e64 v9, s[68:69], 0, v3, s[68:69]
	v_add_co_u32_e64 v16, s[68:69], s8, v28
	global_load_dwordx4 v[4:7], v96, s[0:1]
	global_load_dwordx4 v[12:15], v96, s[82:83]
	v_addc_co_u32_e64 v17, s[68:69], 0, v29, s[68:69]
	global_load_dwordx4 v[8:11], v[8:9], off
	s_nop 0
	global_load_dwordx4 v[16:19], v[16:17], off
	s_nop 0
	global_load_dwordx4 v[24:27], v224, s[0:1]
	global_load_dwordx4 v[20:23], v224, s[82:83]
	s_movk_i32 s0, 0x6000
	v_add_co_u32_e64 v2, s[68:69], s0, v2
	s_lshl_b64 s[4:5], s[4:5], 13
	s_nop 0
	v_addc_co_u32_e64 v3, s[68:69], 0, v3, s[68:69]
	global_load_dwordx4 v[32:35], v[2:3], off
	v_add_co_u32_e64 v2, s[68:69], s0, v28
	s_or_b32 s4, s4, s81
	s_nop 0
	v_addc_co_u32_e64 v3, s[68:69], 0, v29, s[68:69]
	s_lshl_b32 s0, s80, 7
	v_or_b32_e32 v0, s4, v98
	global_load_dwordx4 v[36:39], v[2:3], off
	v_or_b32_e32 v2, s0, v106
	v_mul_lo_u32 v3, v0, s9
	v_mov_b32_e32 v1, s5
	v_or_b32_e32 v3, v3, v2
	v_lshl_add_u32 v3, v3, 1, v229
	v_lshl_add_u64 v[0:1], v[0:1], 2, s[12:13]
	buffer_load_dwordx4 v[50:53], v3, s[88:91], 0 offen
	buffer_load_dwordx4 v[54:57], v3, s[88:91], 0 offen offset:128
	buffer_load_dwordx4 v[58:61], v3, s[88:91], 0 offen offset:1024
	buffer_load_dwordx4 v[62:65], v3, s[88:91], 0 offen offset:1152
	v_lshl_add_u64 v[66:67], s[4:5], 0, v[100:101]
	global_load_dword v0, v[0:1], off
	v_mul_lo_u32 v204, v66, s9
	v_or_b32_e32 v204, v204, v2
	v_lshl_add_u32 v204, v204, 1, v229
	v_lshl_add_u64 v[66:67], v[66:67], 2, s[12:13]
	buffer_load_dwordx4 v[44:47], v204, s[88:91], 0 offen
	buffer_load_dwordx4 v[40:43], v204, s[88:91], 0 offen offset:128
	buffer_load_dwordx4 v[28:31], v204, s[88:91], 0 offen offset:1024
	buffer_load_dwordx4 v[240:243], v204, s[88:91], 0 offen offset:1152
	global_load_dword v66, v[66:67], off
	s_waitcnt vmcnt(18)
	s_add_i32 s101, s80, 1
	s_cmp_eq_u32 s100, s101
	s_cbranch_scc0 .Lp4_log
	v_mov_b32_e32 v48, s98
	v_mov_b32_e32 v105, s99
	s_branch .Lp4_logdone

; __device__ __forceinline__ u32x4 ws_load16(const WsRef& w, unsigned byte_off) { return __builtin_bit_cast(u32x4, __builtin_amdgcn_raw_buffer_load_b128(w.r, byte_off, 0, 0)); }
; __device__ __forceinline__ float fexp2(float x) { return __builtin_amdgcn_exp2f(x); }
; __device__ __forceinline__ void ret_unit(LAS unsigned char* lds, int u, const bf16* PROJ, const int* pos, const float* dec_f, const float* dec_b, const bf16* ST,
;                                          const float* gn_w, const float* gn_b, bf16* MIX, int tid, const WsRef& wsr) {
;     ...
;     for (int ii = 0; ii < 2; ++ii) { const int it = tid + 512 * ii, dc = it & 7, j = it >> 3; const unsigned qo = (unsigned)WS_PROJ + (unsigned)(((unsigned)(row0 + j) * INC + h * 128 + dc * 8) * 2u);
;         rq1[ii] = ws_load16(wsr, qo); rq2[ii] = ws_load16(wsr, qo + 128u); rk1[ii] = ws_load16(wsr, qo + 1024u); rk2[ii] = ws_load16(wsr, qo + 1152u); rp[ii] = (float)pos[row0 + j]; }
; #pragma unroll
;     for (int ii = 0; ii < 2; ++ii) { const int it = tid + 512 * ii, dc = it & 7, j = it >> 3;
;         const u32x4 q1 = rq1[ii], q2 = rq2[ii], k1 = rk1[ii], k2 = rk2[ii];
;         const float p = rp[ii];
;         float sn[8], cs[8];
; #pragma unroll
;         for (int e = 0; e < 8; ++e) { const int i = dc * 8 + e; const float inv = fexp2(-(float)i * 0.20762050593046015f); fast_sincos(p * inv, sn[e], cs[e]); }
.Lp4_logdone:
	v_mul_f32_e32 v230, 0xbfb8aa3b, v48
	v_cndmask_b32_e64 v89, v105, v230, s[30:31]
	v_cndmask_b32_e64 v94, v105, v230, s[56:57]
	v_cndmask_b32_e64 v95, v105, v230, s[58:59]
	v_mul_f32_e32 v89, v89, v137
	v_cndmask_b32_e64 v92, v105, v230, s[74:75]
	v_cndmask_b32_e64 v93, v105, v230, s[76:77]
	v_mul_f32_e32 v94, v94, v142
	v_mul_f32_e32 v95, v95, v143
	v_exp_f32_e32 v89, v89
	v_mul_f32_e32 v92, v92, v140
	v_mul_f32_e32 v93, v93, v141
	v_exp_f32_e32 v94, v94
	v_exp_f32_e32 v95, v95
	v_exp_f32_e32 v92, v92
	v_exp_f32_e32 v93, v93
	v_cndmask_b32_e64 v130, v105, v230, s[60:61]
	v_cndmask_b32_e64 v131, v105, v230, s[62:63]
	v_cndmask_b32_e64 v48, v105, v230, s[42:43]
	v_mul_f32_e32 v130, v130, v144
	v_mul_f32_e32 v131, v131, v145
	v_mul_f32_e32 v48, v48, v127
	v_exp_f32_e32 v130, v130
	v_exp_f32_e32 v131, v131
	v_exp_f32_e32 v48, v48
	v_cndmask_b32_e64 v90, v105, v230, s[34:35]
	v_cndmask_b32_e64 v91, v105, v230, s[38:39]
	v_mul_f32_e32 v90, v90, v138
	v_mul_f32_e32 v91, v91, v139
	v_exp_f32_e32 v90, v90
	v_exp_f32_e32 v91, v91
	v_cndmask_b32_e64 v238, v105, v230, s[94:95]
	v_mul_f32_e32 v238, v238, v154
	v_exp_f32_e32 v238, v238
	v_cndmask_b32_e64 v234, v105, v230, s[78:79]
	v_cndmask_b32_e64 v235, v105, v230, s[2:3]
	v_cndmask_b32_e64 v236, v105, v230, s[92:93]
	v_cndmask_b32_e32 v237, v105, v230, vcc
	v_mul_f32_e32 v234, v234, v150
	v_mul_f32_e32 v235, v235, v151
	v_mul_f32_e32 v236, v236, v152
	v_mul_f32_e32 v237, v237, v153
	v_exp_f32_e32 v234, v234
	v_exp_f32_e32 v235, v235
	v_exp_f32_e32 v236, v236
	v_exp_f32_e32 v237, v237
	v_cndmask_b32_e64 v132, v105, v230, s[64:65]
	v_cndmask_b32_e64 v133, v105, v230, s[14:15]
	v_cndmask_b32_e64 v232, v105, v230, s[16:17]
	v_cndmask_b32_e64 v233, v105, v230, s[24:25]
	v_mul_f32_e32 v132, v132, v146
	v_mul_f32_e32 v133, v133, v147
	v_mul_f32_e32 v232, v232, v148
	v_mul_f32_e32 v233, v233, v149
	v_exp_f32_e32 v132, v132
	v_exp_f32_e32 v133, v133
	v_exp_f32_e32 v232, v232
	v_exp_f32_e32 v233, v233
	s_mov_b32 s1, 0x800000
	s_add_i32 s73, s73, s40
	s_cmpk_lt_i32 s73, 0x200
	s_waitcnt vmcnt(9)
	v_lshlrev_b32_e32 v82, 16, v50
	s_waitcnt vmcnt(8)
	v_lshlrev_b32_e32 v84, 16, v54
	v_and_b32_e32 v85, 0xffff0000, v54
	v_and_b32_e32 v83, 0xffff0000, v50
	s_waitcnt vmcnt(5)
	v_cvt_f32_i32_e32 v49, v0
	v_mul_f32_e32 v70, v109, v49
	v_mul_f32_e32 v71, 0.15915494, v70
	v_rndne_f32_e32 v71, v71
	v_fmac_f32_e32 v70, 0xc0c90000, v71
	v_fmac_f32_e32 v70, 0xbafdaa22, v71
	v_mul_f32_e32 v71, 0.15915494, v70
	v_sin_f32_e32 v70, v71
	v_cos_f32_e32 v72, v71
	v_mul_f32_e32 v71, v110, v49
	v_mul_f32_e32 v73, 0.15915494, v71
	v_mul_f32_e32 v74, v111, v49
	v_rndne_f32_e32 v73, v73
	v_mul_f32_e32 v75, 0.15915494, v74
	v_fmac_f32_e32 v71, 0xc0c90000, v73
	v_rndne_f32_e32 v75, v75
	v_fmac_f32_e32 v71, 0xbafdaa22, v73
	v_fmac_f32_e32 v74, 0xc0c90000, v75
	v_mul_f32_e32 v73, 0.15915494, v71
	v_fmac_f32_e32 v74, 0xbafdaa22, v75
	v_sin_f32_e32 v71, v73
	v_mul_f32_e32 v75, 0.15915494, v74
	v_cos_f32_e32 v73, v73
	v_sin_f32_e32 v74, v75
	v_cos_f32_e32 v76, v75
	v_mul_f32_e32 v75, v112, v49
	v_mul_f32_e32 v77, 0.15915494, v75
	v_rndne_f32_e32 v77, v77
	v_mul_f32_e32 v78, v113, v49
	v_fmac_f32_e32 v75, 0xc0c90000, v77
	v_mul_f32_e32 v79, 0.15915494, v78
	v_fmac_f32_e32 v75, 0xbafdaa22, v77
	v_rndne_f32_e32 v79, v79
	v_mul_f32_e32 v77, 0.15915494, v75
	v_fmac_f32_e32 v78, 0xc0c90000, v79
	v_sin_f32_e32 v75, v77
	v_fmac_f32_e32 v78, 0xbafdaa22, v79
	v_cos_f32_e32 v77, v77
	v_mul_f32_e32 v79, 0.15915494, v78
	v_sin_f32_e32 v78, v79
	v_cos_f32_e32 v80, v79
	s_waitcnt vmcnt(0)
	v_cvt_f32_i32_e32 v88, v66
	v_mul_f32_e32 v66, v107, v49
	v_mul_f32_e32 v67, 0.15915494, v66
	v_rndne_f32_e32 v67, v67
	v_fmac_f32_e32 v66, 0xc0c90000, v67
	v_fmac_f32_e32 v66, 0xbafdaa22, v67
	v_mul_f32_e32 v67, 0.15915494, v66
	v_sin_f32_e32 v66, v67
	v_cos_f32_e32 v68, v67
	v_mul_f32_e32 v67, v108, v49
	v_mul_f32_e32 v69, 0.15915494, v67
	v_rndne_f32_e32 v69, v69
	v_fmac_f32_e32 v67, 0xc0c90000, v69
	v_fmac_f32_e32 v67, 0xbafdaa22, v69
	v_mul_f32_e32 v69, 0.15915494, v67
	v_sin_f32_e32 v67, v69
	v_cos_f32_e32 v69, v69
	v_mul_f32_e32 v49, v114, v49
	v_mul_f32_e32 v79, 0.15915494, v49
	v_pk_mul_f32 v[86:87], v[66:67], v[84:85]
	v_rndne_f32_e32 v79, v79
	v_pk_fma_f32 v[86:87], v[68:69], v[82:83], v[86:87] neg_lo:[0,0,1] neg_hi:[0,0,1]
	v_pk_mul_f32 v[82:83], v[66:67], v[82:83]
	v_cvt_pk_bf16_f32 v50, v86, v87
	v_pk_fma_f32 v[82:83], v[68:69], v[84:85], v[82:83]
	v_lshlrev_b32_e32 v84, 16, v62
	v_cvt_pk_bf16_f32 v54, v82, v83
	v_lshlrev_b32_e32 v82, 16, v58
	v_and_b32_e32 v83, 0xffff0000, v58
	v_and_b32_e32 v85, 0xffff0000, v62
	v_pk_mul_f32 v[82:83], v[82:83], s[10:11] op_sel_hi:[1,0]
	v_pk_mul_f32 v[84:85], v[84:85], s[10:11] op_sel_hi:[1,0]
	v_fmac_f32_e32 v49, 0xc0c90000, v79
	v_pk_mul_f32 v[86:87], v[84:85], v[66:67]
	v_pk_mul_f32 v[66:67], v[82:83], v[66:67]
	v_pk_fma_f32 v[86:87], v[82:83], v[68:69], v[86:87] neg_lo:[0,0,1] neg_hi:[0,0,1]
	v_pk_fma_f32 v[66:67], v[84:85], v[68:69], v[66:67]
	v_lshlrev_b32_e32 v68, 16, v55
	v_and_b32_e32 v69, 0xffff0000, v55
	v_cvt_pk_bf16_f32 v62, v66, v67
	v_lshlrev_b32_e32 v66, 16, v51
	v_and_b32_e32 v67, 0xffff0000, v51
	v_pk_mul_f32 v[82:83], v[70:71], v[68:69]
	v_fmac_f32_e32 v49, 0xbafdaa22, v79
	v_pk_fma_f32 v[82:83], v[72:73], v[66:67], v[82:83] neg_lo:[0,0,1] neg_hi:[0,0,1]
	v_pk_mul_f32 v[66:67], v[70:71], v[66:67]
	v_cvt_pk_bf16_f32 v51, v82, v83
	v_pk_fma_f32 v[66:67], v[72:73], v[68:69], v[66:67]
	v_lshlrev_b32_e32 v68, 16, v63
	v_and_b32_e32 v69, 0xffff0000, v63
	v_cvt_pk_bf16_f32 v55, v66, v67
	v_lshlrev_b32_e32 v66, 16, v59
	v_and_b32_e32 v67, 0xffff0000, v59
	v_pk_mul_f32 v[68:69], v[68:69], s[10:11] op_sel_hi:[1,0]
; #define LAS __attribute__((address_space(3)))
; __device__ __forceinline__ unsigned pk2(float lo, float hi) { return pg8::cvt_pk_bf16(lo, hi); }
; __device__ __forceinline__ float bflo(unsigned w) { return __uint_as_float(w << 16); }
; __device__ __forceinline__ float bfhi(unsigned w) { return __uint_as_float(w & 0xffff0000u); }
; __device__ __forceinline__ u32x4 ws_load16(const WsRef& w, unsigned byte_off) { return __builtin_bit_cast(u32x4, __builtin_amdgcn_raw_buffer_load_b128(w.r, byte_off, 0, 0)); }
; __device__ __forceinline__ void ret_unit(LAS unsigned char* lds, int u, const bf16* PROJ, const int* pos, const float* dec_f, const float* dec_b, const bf16* ST,
;                                          const float* gn_w, const float* gn_b, bf16* MIX, int tid, const WsRef& wsr) {
;     ...
;     for (int ii = 0; ii < 2; ++ii) { const int it = tid + 512 * ii, dc = it & 7, j = it >> 3;
;         const u32x4 q1 = rq1[ii], q2 = rq2[ii], k1 = rk1[ii], k2 = rk2[ii];
;         const float p = rp[ii];
;         float sn[8], cs[8];
; #pragma unroll
;         for (int e = 0; e < 8; ++e) { const int i = dc * 8 + e; const float inv = fexp2(-(float)i * 0.20762050593046015f); fast_sincos(p * inv, sn[e], cs[e]); }
;         u32x4 oq1, oq2, ok1, ok2;
; #pragma unroll
;         for (int e = 0; e < 4; ++e) { const int e0 = 2 * e, e1 = 2 * e + 1;
;             const float a0 = bflo(q1[e]), a1 = bfhi(q1[e]), b0 = bflo(q2[e]), b1 = bfhi(q2[e]);
;             oq1[e] = pk2(a0 * cs[e0] - b0 * sn[e0], a1 * cs[e1] - b1 * sn[e1]); oq2[e] = pk2(b0 * cs[e0] + a0 * sn[e0], b1 * cs[e1] + a1 * sn[e1]);
;             const float c0 = bflo(k1[e]) * 0.08838834764831845f, c1 = bfhi(k1[e]) * 0.08838834764831845f, d0 = bflo(k2[e]) * 0.08838834764831845f, d1 = bfhi(k2[e]) * 0.08838834764831845f;
;             ok1[e] = pk2(c0 * cs[e0] - d0 * sn[e0], c1 * cs[e1] - d1 * sn[e1]); ok2[e] = pk2(d0 * cs[e0] + c0 * sn[e0], d1 * cs[e1] + c1 * sn[e1]); }
;         *(LAS u32x4*)(Qs + j * LDT + dc * 8) = oq1; *(LAS u32x4*)(Qs + j * LDT + 64 + dc * 8) = oq2;
;         *(LAS u32x4*)(Ks + j * LDT + dc * 8) = ok1; *(LAS u32x4*)(Ks + j * LDT + 64 + dc * 8) = ok2; }
; #pragma unroll
;     for (int ii = 0; ii < 4; ++ii) { const int it = tid + 512 * ii, ec = it & 15, j = it >> 4; rv[ii] = ws_load16(wsr, (unsigned)WS_PROJ + (unsigned)(((unsigned)(row0 + j) * INC + 1024 + h * 128 + ec * 8) * 2u)); }
	v_pk_mul_f32 v[66:67], v[66:67], s[10:11] op_sel_hi:[1,0]
	v_pk_mul_f32 v[82:83], v[68:69], v[70:71]
	v_mul_f32_e32 v49, 0.15915494, v49
	v_pk_fma_f32 v[82:83], v[66:67], v[72:73], v[82:83] neg_lo:[0,0,1] neg_hi:[0,0,1]
	v_pk_mul_f32 v[66:67], v[66:67], v[70:71]
	v_sin_f32_e32 v79, v49
	v_pk_fma_f32 v[66:67], v[68:69], v[72:73], v[66:67]
	v_lshlrev_b32_e32 v68, 16, v56
	v_and_b32_e32 v69, 0xffff0000, v56
	v_cvt_pk_bf16_f32 v63, v66, v67
	v_lshlrev_b32_e32 v66, 16, v52
	v_and_b32_e32 v67, 0xffff0000, v52
	v_pk_mul_f32 v[70:71], v[74:75], v[68:69]
	v_cos_f32_e32 v81, v49
	v_pk_fma_f32 v[70:71], v[76:77], v[66:67], v[70:71] neg_lo:[0,0,1] neg_hi:[0,0,1]
	v_pk_mul_f32 v[66:67], v[74:75], v[66:67]
	v_cvt_pk_bf16_f32 v52, v70, v71
	v_pk_fma_f32 v[66:67], v[76:77], v[68:69], v[66:67]
	v_lshlrev_b32_e32 v68, 16, v64
	v_and_b32_e32 v69, 0xffff0000, v64
	v_cvt_pk_bf16_f32 v56, v66, v67
	v_lshlrev_b32_e32 v66, 16, v60
	v_and_b32_e32 v67, 0xffff0000, v60
	v_pk_mul_f32 v[68:69], v[68:69], s[10:11] op_sel_hi:[1,0]
	v_pk_mul_f32 v[66:67], v[66:67], s[10:11] op_sel_hi:[1,0]
	v_pk_mul_f32 v[70:71], v[68:69], v[74:75]
	v_mul_f32_e32 v49, v107, v88
	v_pk_fma_f32 v[70:71], v[66:67], v[76:77], v[70:71] neg_lo:[0,0,1] neg_hi:[0,0,1]
	v_pk_mul_f32 v[66:67], v[66:67], v[74:75]
	v_cvt_pk_bf16_f32 v60, v70, v71
	v_pk_fma_f32 v[66:67], v[68:69], v[76:77], v[66:67]
	v_lshlrev_b32_e32 v68, 16, v57
	v_and_b32_e32 v69, 0xffff0000, v57
	v_cvt_pk_bf16_f32 v64, v66, v67
	v_lshlrev_b32_e32 v66, 16, v53
	v_and_b32_e32 v67, 0xffff0000, v53
	v_pk_mul_f32 v[70:71], v[78:79], v[68:69]
	v_cvt_pk_bf16_f32 v58, v86, v87
	v_pk_fma_f32 v[70:71], v[80:81], v[66:67], v[70:71] neg_lo:[0,0,1] neg_hi:[0,0,1]
	v_pk_mul_f32 v[66:67], v[78:79], v[66:67]
	v_cvt_pk_bf16_f32 v53, v70, v71
	v_pk_fma_f32 v[66:67], v[80:81], v[68:69], v[66:67]
	v_lshlrev_b32_e32 v68, 16, v65
	v_and_b32_e32 v69, 0xffff0000, v65
	v_cvt_pk_bf16_f32 v57, v66, v67
	v_lshlrev_b32_e32 v66, 16, v61
	v_and_b32_e32 v67, 0xffff0000, v61
	v_pk_mul_f32 v[68:69], v[68:69], s[10:11] op_sel_hi:[1,0]
	v_pk_mul_f32 v[66:67], v[66:67], s[10:11] op_sel_hi:[1,0]
	v_pk_mul_f32 v[70:71], v[68:69], v[78:79]
	v_cvt_pk_bf16_f32 v59, v82, v83
	v_pk_fma_f32 v[70:71], v[66:67], v[80:81], v[70:71] neg_lo:[0,0,1] neg_hi:[0,0,1]
	v_pk_mul_f32 v[66:67], v[66:67], v[78:79]
	v_cvt_pk_bf16_f32 v61, v70, v71
	v_pk_fma_f32 v[66:67], v[68:69], v[80:81], v[66:67]
	v_lshlrev_b32_e32 v68, 16, v40
	v_cvt_pk_bf16_f32 v65, v66, v67
	ds_write_b128 v115, v[50:53]
	ds_write_b128 v115, v[54:57] offset:128
	ds_write_b128 v115, v[58:61] offset:34816
	ds_write_b128 v115, v[62:65] offset:34944
	v_or_b32_e32 v87, s0, v222
	v_or_b32_e32 v204, s4, v99
	v_mul_lo_u32 v204, v204, s9
	v_add_lshl_u32 v204, v204, v87, 1
	v_add_u32_e32 v204, v204, v229
	buffer_load_dwordx4 v[72:75], v204, s[88:91], 0 offen
	v_or_b32_e32 v239, s4, v117
	v_mul_lo_u32 v239, v239, s9
	v_add_lshl_u32 v239, v239, v87, 1
	v_add_u32_e32 v239, v239, v229
	buffer_load_dwordx4 v[78:81], v239, s[88:91], 0 offen
	v_or_b32_e32 v77, s4, v118
	v_mul_lo_u32 v77, v77, s9
	v_add_lshl_u32 v77, v77, v87, 1
	v_add_u32_e32 v77, v77, v229
	buffer_load_dwordx4 v[82:85], v77, s[88:91], 0 offen
	v_add_u32_e32 v204, s4, v119
	v_mul_lo_u32 v204, v204, s9
	v_add_lshl_u32 v204, v204, v87, 1
	v_add_u32_e32 v204, v204, v229
	buffer_load_dwordx4 v[248:251], v204, s[88:91], 0 offen
	v_mul_f32_e32 v50, 0.15915494, v49
	v_rndne_f32_e32 v50, v50
	v_fmac_f32_e32 v49, 0xc0c90000, v50
	v_fmac_f32_e32 v49, 0xbafdaa22, v50
	v_mul_f32_e32 v49, 0.15915494, v49
	v_sin_f32_e32 v50, v49
	v_cos_f32_e32 v52, v49
	v_mul_f32_e32 v49, v108, v88
	v_mul_f32_e32 v51, 0.15915494, v49
	v_rndne_f32_e32 v51, v51
	v_fmac_f32_e32 v49, 0xc0c90000, v51
	v_fmac_f32_e32 v49, 0xbafdaa22, v51
	v_mul_f32_e32 v49, 0.15915494, v49
	v_sin_f32_e32 v51, v49
	v_cos_f32_e32 v53, v49
	v_mul_f32_e32 v49, v109, v88
	v_mul_f32_e32 v54, 0.15915494, v49
	v_rndne_f32_e32 v54, v54
	v_fmac_f32_e32 v49, 0xc0c90000, v54
	v_fmac_f32_e32 v49, 0xbafdaa22, v54
	v_mul_f32_e32 v49, 0.15915494, v49
	v_sin_f32_e32 v54, v49
	v_cos_f32_e32 v56, v49
	v_mul_f32_e32 v49, v110, v88
	v_mul_f32_e32 v55, 0.15915494, v49
	v_rndne_f32_e32 v55, v55
	v_fmac_f32_e32 v49, 0xc0c90000, v55
	v_fmac_f32_e32 v49, 0xbafdaa22, v55
	v_mul_f32_e32 v49, 0.15915494, v49
	v_sin_f32_e32 v55, v49
	v_cos_f32_e32 v57, v49
	v_mul_f32_e32 v49, v111, v88
	v_mul_f32_e32 v58, 0.15915494, v49
	v_rndne_f32_e32 v58, v58
	v_fmac_f32_e32 v49, 0xc0c90000, v58
	v_fmac_f32_e32 v49, 0xbafdaa22, v58
	v_mul_f32_e32 v49, 0.15915494, v49
	v_sin_f32_e32 v58, v49
	v_cos_f32_e32 v60, v49
	v_mul_f32_e32 v49, v112, v88
	v_and_b32_e32 v69, 0xffff0000, v40
	v_mul_f32_e32 v59, 0.15915494, v49
	v_lshlrev_b32_e32 v66, 16, v44
	v_and_b32_e32 v67, 0xffff0000, v44
	v_pk_mul_f32 v[70:71], v[50:51], v[68:69]
	v_rndne_f32_e32 v59, v59
	v_pk_fma_f32 v[70:71], v[52:53], v[66:67], v[70:71] neg_lo:[0,0,1] neg_hi:[0,0,1]
	v_pk_mul_f32 v[66:67], v[50:51], v[66:67]
	v_fmac_f32_e32 v49, 0xc0c90000, v59
	v_pk_fma_f32 v[66:67], v[52:53], v[68:69], v[66:67]
	v_fmac_f32_e32 v49, 0xbafdaa22, v59
	v_cvt_pk_bf16_f32 v44, v66, v67
	v_lshlrev_b32_e32 v66, 16, v28
	v_and_b32_e32 v67, 0xffff0000, v28
	v_lshlrev_b32_e32 v68, 16, v240
	v_and_b32_e32 v69, 0xffff0000, v240
	v_mul_f32_e32 v49, 0.15915494, v49
	v_pk_mul_f32 v[66:67], v[66:67], s[10:11] op_sel_hi:[1,0]
	v_pk_mul_f32 v[68:69], v[68:69], s[10:11] op_sel_hi:[1,0]
	v_sin_f32_e32 v59, v49
	v_cos_f32_e32 v61, v49
	v_mul_f32_e32 v49, v113, v88
	v_cvt_pk_bf16_f32 v40, v70, v71
	v_pk_mul_f32 v[70:71], v[68:69], v[50:51]
	v_pk_mul_f32 v[50:51], v[66:67], v[50:51]
	v_mul_f32_e32 v62, 0.15915494, v49
; #define LAS __attribute__((address_space(3)))
; __device__ __forceinline__ unsigned pk2(float lo, float hi) { return pg8::cvt_pk_bf16(lo, hi); }
; __device__ __forceinline__ void ret_unit(LAS unsigned char* lds, int u, const bf16* PROJ, const int* pos, const float* dec_f, const float* dec_b, const bf16* ST,
;                                          const float* gn_w, const float* gn_b, bf16* MIX, int tid, const WsRef& wsr) {
;     ...
;     for (int ii = 0; ii < 2; ++ii) { const int it = tid + 512 * ii, dc = it & 7, j = it >> 3;
;         const u32x4 q1 = rq1[ii], q2 = rq2[ii], k1 = rk1[ii], k2 = rk2[ii];
;         const float p = rp[ii];
;         float sn[8], cs[8];
; #pragma unroll
;         for (int e = 0; e < 8; ++e) { const int i = dc * 8 + e; const float inv = fexp2(-(float)i * 0.20762050593046015f); fast_sincos(p * inv, sn[e], cs[e]); }
;         u32x4 oq1, oq2, ok1, ok2;
; #pragma unroll
;         for (int e = 0; e < 4; ++e) { const int e0 = 2 * e, e1 = 2 * e + 1;
;             const float a0 = bflo(q1[e]), a1 = bfhi(q1[e]), b0 = bflo(q2[e]), b1 = bfhi(q2[e]);
;             oq1[e] = pk2(a0 * cs[e0] - b0 * sn[e0], a1 * cs[e1] - b1 * sn[e1]); oq2[e] = pk2(b0 * cs[e0] + a0 * sn[e0], b1 * cs[e1] + a1 * sn[e1]);
;             const float c0 = bflo(k1[e]) * 0.08838834764831845f, c1 = bfhi(k1[e]) * 0.08838834764831845f, d0 = bflo(k2[e]) * 0.08838834764831845f, d1 = bfhi(k2[e]) * 0.08838834764831845f;
;             ok1[e] = pk2(c0 * cs[e0] - d0 * sn[e0], c1 * cs[e1] - d1 * sn[e1]); ok2[e] = pk2(d0 * cs[e0] + c0 * sn[e0], d1 * cs[e1] + c1 * sn[e1]); }
;         *(LAS u32x4*)(Qs + j * LDT + dc * 8) = oq1; *(LAS u32x4*)(Qs + j * LDT + 64 + dc * 8) = oq2;
;         *(LAS u32x4*)(Ks + j * LDT + dc * 8) = ok1; *(LAS u32x4*)(Ks + j * LDT + 64 + dc * 8) = ok2; }
; #pragma unroll
;     for (int ii = 0; ii < 4; ++ii) { const int it = tid + 512 * ii, ec = it & 15, j = it >> 4; rv[ii] = ws_load16(wsr, (unsigned)WS_PROJ + (unsigned)(((unsigned)(row0 + j) * INC + 1024 + h * 128 + ec * 8) * 2u)); }
; #pragma unroll
;     for (int ii = 0; ii < 4; ++ii) { const int it = tid + 512 * ii, ec = it & 15, j = it >> 4; const u32x4 w = rv[ii];
;         const int jsw = (((j >> 3) ^ (ec & 7)) << 3) | (j & 7);
; #pragma unroll
;         for (int e = 0; e < 4; ++e) { VT[(ec * 8 + 2 * e) * LDT + jsw] = (bf16)(w[e] & 0xffffu); VT[(ec * 8 + 2 * e + 1) * LDT + jsw] = (bf16)(w[e] >> 16); } }
	v_pk_fma_f32 v[70:71], v[66:67], v[52:53], v[70:71] neg_lo:[0,0,1] neg_hi:[0,0,1]
	v_pk_fma_f32 v[50:51], v[68:69], v[52:53], v[50:51]
	v_lshlrev_b32_e32 v52, 16, v41
	v_and_b32_e32 v53, 0xffff0000, v41
	v_rndne_f32_e32 v62, v62
	v_cvt_pk_bf16_f32 v28, v50, v51
	v_lshlrev_b32_e32 v50, 16, v45
	v_and_b32_e32 v51, 0xffff0000, v45
	v_pk_mul_f32 v[66:67], v[54:55], v[52:53]
	v_fmac_f32_e32 v49, 0xc0c90000, v62
	v_pk_fma_f32 v[66:67], v[56:57], v[50:51], v[66:67] neg_lo:[0,0,1] neg_hi:[0,0,1]
	v_pk_mul_f32 v[50:51], v[54:55], v[50:51]
	v_fmac_f32_e32 v49, 0xbafdaa22, v62
	v_pk_fma_f32 v[50:51], v[56:57], v[52:53], v[50:51]
	v_lshlrev_b32_e32 v52, 16, v241
	v_and_b32_e32 v53, 0xffff0000, v241
	v_mul_f32_e32 v49, 0.15915494, v49
	v_cvt_pk_bf16_f32 v45, v50, v51
	v_lshlrev_b32_e32 v50, 16, v29
	v_and_b32_e32 v51, 0xffff0000, v29
	v_pk_mul_f32 v[52:53], v[52:53], s[10:11] op_sel_hi:[1,0]
	v_sin_f32_e32 v62, v49
	v_cos_f32_e32 v64, v49
	v_mul_f32_e32 v49, v114, v88
	v_cvt_pk_bf16_f32 v41, v66, v67
	v_pk_mul_f32 v[50:51], v[50:51], s[10:11] op_sel_hi:[1,0]
	v_pk_mul_f32 v[66:67], v[52:53], v[54:55]
	v_mul_f32_e32 v63, 0.15915494, v49
	v_pk_fma_f32 v[66:67], v[50:51], v[56:57], v[66:67] neg_lo:[0,0,1] neg_hi:[0,0,1]
	v_pk_mul_f32 v[50:51], v[50:51], v[54:55]
	v_rndne_f32_e32 v63, v63
	v_pk_fma_f32 v[50:51], v[52:53], v[56:57], v[50:51]
	v_lshlrev_b32_e32 v52, 16, v42
	v_and_b32_e32 v53, 0xffff0000, v42
	v_fmac_f32_e32 v49, 0xc0c90000, v63
	v_cvt_pk_bf16_f32 v29, v50, v51
	v_lshlrev_b32_e32 v50, 16, v46
	v_and_b32_e32 v51, 0xffff0000, v46
	v_pk_mul_f32 v[54:55], v[58:59], v[52:53]
	v_fmac_f32_e32 v49, 0xbafdaa22, v63
	v_pk_fma_f32 v[54:55], v[60:61], v[50:51], v[54:55] neg_lo:[0,0,1] neg_hi:[0,0,1]
	v_pk_mul_f32 v[50:51], v[58:59], v[50:51]
	v_mul_f32_e32 v49, 0.15915494, v49
	v_pk_fma_f32 v[50:51], v[60:61], v[52:53], v[50:51]
	v_lshlrev_b32_e32 v52, 16, v242
	v_and_b32_e32 v53, 0xffff0000, v242
	v_sin_f32_e32 v63, v49
	v_cvt_pk_bf16_f32 v46, v50, v51
	v_lshlrev_b32_e32 v50, 16, v30
	v_and_b32_e32 v51, 0xffff0000, v30
	v_pk_mul_f32 v[52:53], v[52:53], s[10:11] op_sel_hi:[1,0]
	v_cos_f32_e32 v65, v49
	v_cvt_pk_bf16_f32 v42, v54, v55
	v_pk_mul_f32 v[50:51], v[50:51], s[10:11] op_sel_hi:[1,0]
	v_pk_mul_f32 v[54:55], v[52:53], v[58:59]
	v_cvt_pk_bf16_f32 v0, v70, v71
	v_pk_fma_f32 v[54:55], v[50:51], v[60:61], v[54:55] neg_lo:[0,0,1] neg_hi:[0,0,1]
	v_pk_mul_f32 v[50:51], v[50:51], v[58:59]
	v_cvt_pk_bf16_f32 v2, v54, v55
	v_pk_fma_f32 v[50:51], v[52:53], v[60:61], v[50:51]
	v_lshlrev_b32_e32 v52, 16, v43
	v_and_b32_e32 v53, 0xffff0000, v43
	v_cvt_pk_bf16_f32 v30, v50, v51
	v_lshlrev_b32_e32 v50, 16, v47
	v_and_b32_e32 v51, 0xffff0000, v47
	v_pk_mul_f32 v[54:55], v[62:63], v[52:53]
	v_cvt_pk_bf16_f32 v1, v66, v67
	v_pk_fma_f32 v[54:55], v[64:65], v[50:51], v[54:55] neg_lo:[0,0,1] neg_hi:[0,0,1]
	v_pk_mul_f32 v[50:51], v[62:63], v[50:51]
	v_cvt_pk_bf16_f32 v43, v54, v55
	v_pk_fma_f32 v[50:51], v[64:65], v[52:53], v[50:51]
	v_lshlrev_b32_e32 v52, 16, v243
	v_and_b32_e32 v53, 0xffff0000, v243
	v_cvt_pk_bf16_f32 v47, v50, v51
	v_lshlrev_b32_e32 v50, 16, v31
	v_and_b32_e32 v51, 0xffff0000, v31
	v_pk_mul_f32 v[52:53], v[52:53], s[10:11] op_sel_hi:[1,0]
	v_pk_mul_f32 v[50:51], v[50:51], s[10:11] op_sel_hi:[1,0]
	v_pk_mul_f32 v[54:55], v[52:53], v[62:63]
	v_add_u32_e32 v49, v124, v125
	v_pk_fma_f32 v[54:55], v[50:51], v[64:65], v[54:55] neg_lo:[0,0,1] neg_hi:[0,0,1]
	v_pk_mul_f32 v[50:51], v[50:51], v[62:63]
	v_cvt_pk_bf16_f32 v3, v54, v55
	v_pk_fma_f32 v[50:51], v[52:53], v[64:65], v[50:51]
	v_cndmask_b32_e64 v86, v105, v230, s[66:67]
	v_cvt_pk_bf16_f32 v31, v50, v51
	ds_write_b128 v116, v[40:43]
	ds_write_b128 v116, v[44:47] offset:128
	ds_write_b128 v116, v[0:3] offset:34816
	ds_write_b128 v116, v[28:31] offset:34944
	s_waitcnt vmcnt(3)
	ds_write_b16 v120, v72
	ds_write_b16_d16_hi v120, v72 offset:272
	ds_write_b16 v120, v73 offset:544
	ds_write_b16_d16_hi v120, v73 offset:816
	ds_write_b16 v120, v74 offset:1088
	ds_write_b16_d16_hi v120, v74 offset:1360
	ds_write_b16 v120, v75 offset:1632
	ds_write_b16_d16_hi v120, v75 offset:1904
	s_waitcnt vmcnt(2)
	ds_write_b16 v121, v78
	ds_write_b16_d16_hi v121, v78 offset:272
	ds_write_b16 v121, v79 offset:544
	ds_write_b16_d16_hi v121, v79 offset:816
	ds_write_b16 v121, v80 offset:1088
	ds_write_b16_d16_hi v121, v80 offset:1360
	ds_write_b16 v121, v81 offset:1632
	ds_write_b16_d16_hi v121, v81 offset:1904
	s_waitcnt vmcnt(1)
	ds_write_b16 v122, v82
	ds_write_b16_d16_hi v122, v82 offset:272
	ds_write_b16 v122, v83 offset:544
	ds_write_b16_d16_hi v122, v83 offset:816
	ds_write_b16 v122, v84 offset:1088
	ds_write_b16_d16_hi v122, v84 offset:1360
	ds_write_b16 v122, v85 offset:1632
	ds_write_b16_d16_hi v122, v85 offset:1904
	s_waitcnt vmcnt(0)
	ds_write_b16 v123, v248
	ds_write_b16_d16_hi v123, v248 offset:272
	ds_write_b16 v123, v249 offset:544
	ds_write_b16_d16_hi v123, v249 offset:816
	ds_write_b16 v123, v250 offset:1088
	ds_write_b16_d16_hi v123, v250 offset:1360
	ds_write_b16 v123, v251 offset:1632
	ds_write_b16_d16_hi v123, v251 offset:1904
	s_waitcnt lgkmcnt(0)
	s_barrier
; #define LAS __attribute__((address_space(3)))
; __device__ __forceinline__ float fexp2(float x) { return __builtin_amdgcn_exp2f(x); }
; #define MFMA16(a, b, c) __builtin_amdgcn_mfma_f32_16x16x32_bf16((a), (b), (c), 0, 0, 0)
; __device__ __forceinline__ void ret_unit(LAS unsigned char* lds, int u, const bf16* PROJ, const int* pos, const float* dec_f, const float* dec_b, const bf16* ST,
;                                          const float* gn_w, const float* gn_b, bf16* MIX, int tid, const WsRef& wsr) {
;     ...
;     const int q = wave * 16 + fr;
;     bf16x8 qf[4];
; #pragma unroll
;     for (int kk = 0; kk < 4; ++kk) qf[kk] = *(const LAS bf16x8*)(Qs + q * LDT + kk * 32 + fq * 8);
;     f32x4 s[8];
; #pragma unroll
;     for (int n = 0; n < 8; ++n) s[n] = (f32x4){0.f, 0.f, 0.f, 0.f};
; #pragma unroll
;     for (int kk = 0; kk < 4; ++kk)
; #pragma unroll
;         for (int n = 0; n < 8; ++n) { const bf16x8 kf = *(const LAS bf16x8*)(Ks + (n * 16 + fr) * LDT + kk * 32 + fq * 8); s[n] = MFMA16(kf, qf[kk], s[n]); }
;     bf16x8 pf[4];
; #pragma unroll
;     for (int n = 0; n < 8; ++n) {
; #pragma unroll
;         for (int r = 0; r < 4; ++r) { const int key = n * 16 + 4 * fq + r; const int df = q - key; const float f = df >= 0 ? fexp2(lgf2 * (float)df) : fexp2(lgb2 * (float)(-df)); s[n][r] *= f; } }
	ds_read_b128 v[44:47], v225
	ds_read_b128 v[40:43], v225 offset:64
	ds_read_b128 v[28:31], v225 offset:128
	ds_read_b128 v[0:3], v225 offset:192
	ds_read_b128 v[50:53], v226 offset:34816
	ds_read_b128 v[54:57], v226 offset:39168
	ds_read_b128 v[82:85], v226 offset:34880
	s_waitcnt lgkmcnt(2)
	v_mfma_f32_16x16x32_bf16 v[50:53], v[50:53], v[44:47], 0
	ds_read_b128 v[58:61], v226 offset:43520
	ds_read_b128 v[62:65], v226 offset:47872
	ds_read_b128 v[66:69], v226 offset:52224
	s_waitcnt lgkmcnt(3)
	v_mfma_f32_16x16x32_bf16 v[50:53], v[82:85], v[40:43], v[50:53]
	ds_read_b128 v[82:85], v226 offset:39232
	ds_read_b128 v[70:73], v49 offset:34816
	ds_read_b128 v[74:77], v49 offset:39168
	v_mfma_f32_16x16x32_bf16 v[54:57], v[54:57], v[44:47], 0
	ds_read_b128 v[78:81], v49 offset:43520
	v_cndmask_b32_e64 v87, v105, v230, s[26:27]
	v_cndmask_b32_e64 v88, v105, v230, s[28:29]
	s_waitcnt lgkmcnt(3)
	v_mfma_f32_16x16x32_bf16 v[54:57], v[82:85], v[40:43], v[54:57]
	ds_read_b128 v[82:85], v226 offset:43584
	v_mul_f32_e32 v86, v86, v134
	v_mul_f32_e32 v87, v87, v135
	v_mfma_f32_16x16x32_bf16 v[58:61], v[58:61], v[44:47], 0
	v_mul_f32_e32 v88, v88, v136
	v_exp_f32_e32 v86, v86
	v_exp_f32_e32 v87, v87
	s_waitcnt lgkmcnt(0)
	v_mfma_f32_16x16x32_bf16 v[58:61], v[82:85], v[40:43], v[58:61]
	ds_read_b128 v[82:85], v226 offset:47936
	v_exp_f32_e32 v88, v88
	v_readlane_b32 s68, v255, 4
	v_mfma_f32_16x16x32_bf16 v[62:65], v[62:65], v[44:47], 0
	v_readlane_b32 s69, v255, 5
	s_waitcnt lgkmcnt(0)
	v_mfma_f32_16x16x32_bf16 v[62:65], v[82:85], v[40:43], v[62:65]
	ds_read_b128 v[82:85], v226 offset:52288
	v_cndmask_b32_e64 v239, v105, v230, s[68:69]
	v_readlane_b32 s68, v255, 50
	v_mfma_f32_16x16x32_bf16 v[66:69], v[66:69], v[44:47], 0
	v_readlane_b32 s69, v255, 51
	v_mul_f32_e32 v239, v239, v155
	v_exp_f32_e32 v239, v239
	s_waitcnt lgkmcnt(0)
	v_mfma_f32_16x16x32_bf16 v[66:69], v[82:85], v[40:43], v[66:69]
	ds_read_b128 v[82:85], v49 offset:34880
	v_cndmask_b32_e64 v240, v105, v230, s[68:69]
	v_readlane_b32 s68, v255, 52
	v_mfma_f32_16x16x32_bf16 v[70:73], v[70:73], v[44:47], 0
	v_readlane_b32 s69, v255, 53
	v_mul_f32_e32 v240, v240, v156
	v_exp_f32_e32 v240, v240
	s_waitcnt lgkmcnt(0)
	v_mfma_f32_16x16x32_bf16 v[70:73], v[82:85], v[40:43], v[70:73]
	ds_read_b128 v[82:85], v49 offset:39232
	v_cndmask_b32_e64 v241, v105, v230, s[68:69]
	v_readlane_b32 s68, v255, 54
	v_mfma_f32_16x16x32_bf16 v[74:77], v[74:77], v[44:47], 0
	v_readlane_b32 s69, v255, 55
	v_mul_f32_e32 v241, v241, v157
	v_exp_f32_e32 v241, v241
	s_waitcnt lgkmcnt(0)
	v_mfma_f32_16x16x32_bf16 v[74:77], v[82:85], v[40:43], v[74:77]
	ds_read_b128 v[82:85], v49 offset:43584
	v_cndmask_b32_e64 v242, v105, v230, s[68:69]
	v_readlane_b32 s68, v255, 56
	v_mfma_f32_16x16x32_bf16 v[78:81], v[78:81], v[44:47], 0
	v_readlane_b32 s69, v255, 57
	v_mul_f32_e32 v242, v242, v158
	v_exp_f32_e32 v242, v242
	s_waitcnt lgkmcnt(0)
	v_mfma_f32_16x16x32_bf16 v[78:81], v[82:85], v[40:43], v[78:81]
	ds_read_b128 v[82:85], v226 offset:34944
	v_cndmask_b32_e64 v243, v105, v230, s[68:69]
	v_mul_f32_e32 v243, v243, v159
	s_waitcnt lgkmcnt(0)
	v_mfma_f32_16x16x32_bf16 v[50:53], v[82:85], v[28:31], v[50:53]
	ds_read_b128 v[82:85], v226 offset:39296
	v_exp_f32_e32 v243, v243
	s_waitcnt lgkmcnt(0)
	v_mfma_f32_16x16x32_bf16 v[54:57], v[82:85], v[28:31], v[54:57]
	ds_read_b128 v[82:85], v226 offset:43648
	s_waitcnt lgkmcnt(0)
	v_mfma_f32_16x16x32_bf16 v[58:61], v[82:85], v[28:31], v[58:61]
	ds_read_b128 v[82:85], v226 offset:48000
	s_waitcnt lgkmcnt(0)
	v_mfma_f32_16x16x32_bf16 v[62:65], v[82:85], v[28:31], v[62:65]
	ds_read_b128 v[82:85], v226 offset:52352
	s_waitcnt lgkmcnt(0)
	v_mfma_f32_16x16x32_bf16 v[66:69], v[82:85], v[28:31], v[66:69]
	ds_read_b128 v[82:85], v49 offset:34944
	s_waitcnt lgkmcnt(0)
	v_mfma_f32_16x16x32_bf16 v[70:73], v[82:85], v[28:31], v[70:73]
	ds_read_b128 v[82:85], v49 offset:39296
	s_waitcnt lgkmcnt(0)
	v_mfma_f32_16x16x32_bf16 v[74:77], v[82:85], v[28:31], v[74:77]
	ds_read_b128 v[82:85], v49 offset:43648
	s_waitcnt lgkmcnt(0)
	v_mfma_f32_16x16x32_bf16 v[78:81], v[82:85], v[28:31], v[78:81]
	ds_read_b128 v[82:85], v226 offset:35008
	s_waitcnt lgkmcnt(0)
	v_mfma_f32_16x16x32_bf16 v[50:53], v[82:85], v[0:3], v[50:53]
	ds_read_b128 v[82:85], v226 offset:39360
	s_waitcnt lgkmcnt(0)
	v_mfma_f32_16x16x32_bf16 v[54:57], v[82:85], v[0:3], v[54:57]
	ds_read_b128 v[82:85], v226 offset:43712
	s_nop 6
	v_pk_mul_f32 v[56:57], v[86:87], v[56:57]
	s_waitcnt lgkmcnt(0)
	v_mfma_f32_16x16x32_bf16 v[58:61], v[82:85], v[0:3], v[58:61]
	ds_read_b128 v[82:85], v226 offset:48064
	s_nop 6
	v_pk_mul_f32 v[58:59], v[88:89], v[58:59]
	s_waitcnt lgkmcnt(0)
	v_mfma_f32_16x16x32_bf16 v[62:65], v[82:85], v[0:3], v[62:65]
	ds_read_b128 v[82:85], v226 offset:52416
	v_pk_mul_f32 v[88:89], v[90:91], v[60:61]
	s_nop 5
	v_pk_mul_f32 v[64:65], v[94:95], v[64:65]
	s_waitcnt lgkmcnt(0)
	v_mfma_f32_16x16x32_bf16 v[66:69], v[82:85], v[0:3], v[66:69]
	ds_read_b128 v[82:85], v49 offset:35008
	v_pk_mul_f32 v[92:93], v[92:93], v[62:63]
	v_cvt_pk_bf16_f32 v63, v56, v57
	v_cvt_pk_bf16_f32 v56, v58, v59
	v_cvt_pk_bf16_f32 v59, v64, v65
	v_add_u32_e32 v64, v160, v161
	ds_read_b64 v[64:65], v64
	s_waitcnt lgkmcnt(1)
	v_mfma_f32_16x16x32_bf16 v[70:73], v[82:85], v[0:3], v[70:73]
	ds_read_b128 v[82:85], v49 offset:39360
	v_cvt_pk_bf16_f32 v58, v92, v93
	v_add_u32_e32 v92, v175, v170
	ds_read_b64 v[92:93], v92
	s_waitcnt lgkmcnt(1)
	v_mfma_f32_16x16x32_bf16 v[74:77], v[82:85], v[0:3], v[74:77]
	ds_read_b128 v[82:85], v49 offset:43712
	v_add_u32_e32 v94, v175, v171
	ds_read_b64 v[94:95], v94
	s_waitcnt lgkmcnt(1)
; #define LAS __attribute__((address_space(3)))
; __device__ __forceinline__ unsigned pk2(float lo, float hi) { return pg8::cvt_pk_bf16(lo, hi); }
; __device__ __forceinline__ float fexp2(float x) { return __builtin_amdgcn_exp2f(x); }
; #define MFMA16(a, b, c) __builtin_amdgcn_mfma_f32_16x16x32_bf16((a), (b), (c), 0, 0, 0)
; __device__ __forceinline__ void ret_unit(LAS unsigned char* lds, int u, const bf16* PROJ, const int* pos, const float* dec_f, const float* dec_b, const bf16* ST,
;                                          const float* gn_w, const float* gn_b, bf16* MIX, int tid, const WsRef& wsr) {
;     ...
;     bf16x8 pf[4];
; #pragma unroll
;     for (int n = 0; n < 8; ++n) {
; #pragma unroll
;         for (int r = 0; r < 4; ++r) { const int key = n * 16 + 4 * fq + r; const int df = q - key; const float f = df >= 0 ? fexp2(lgf2 * (float)df) : fexp2(lgb2 * (float)(-df)); s[n][r] *= f; } }
; #pragma unroll
;     for (int kk = 0; kk < 4; ++kk) { u32x4 w; w.x = pk2(s[2 * kk][0], s[2 * kk][1]); w.y = pk2(s[2 * kk][2], s[2 * kk][3]); w.z = pk2(s[2 * kk + 1][0], s[2 * kk + 1][1]); w.w = pk2(s[2 * kk + 1][2], s[2 * kk + 1][3]);
;         pf[kk] = __builtin_bit_cast(bf16x8, w); }
;     f32x4 o[8];
; #pragma unroll
;     for (int n = 0; n < 8; ++n) o[n] = (f32x4){0.f, 0.f, 0.f, 0.f};
; #pragma unroll
;     for (int kk = 0; kk < 4; ++kk)
; #pragma unroll
;         for (int n = 0; n < 8; ++n) { const int sw = (2 * n + (fr >> 3)) & 7, jc = kk * 4 + (fq >> 1); const LAS bf16* vr = VT + (n * 16 + fr) * LDT + 4 * (fq & 1);
;             const u32x2 lo = *(const LAS u32x2*)(vr + ((jc ^ sw) << 3)), hi = *(const LAS u32x2*)(vr + (((jc + 2) ^ sw) << 3)); u32x4 w; w.x = lo.x; w.y = lo.y; w.z = hi.x; w.w = hi.y;
;             o[n] = MFMA16(__builtin_bit_cast(bf16x8, w), pf[kk], o[n]); }
	v_mfma_f32_16x16x32_bf16 v[78:81], v[82:85], v[0:3], v[78:81]
	v_cndmask_b32_e64 v49, v105, v230, s[44:45]
	v_cndmask_b32_e64 v82, v105, v230, s[46:47]
	v_cndmask_b32_e64 v83, v105, v230, s[48:49]
	v_mul_f32_e32 v49, v49, v129
	v_mul_f32_e32 v82, v82, v231
	v_mul_f32_e32 v83, v83, v252
	v_exp_f32_e32 v49, v49
	v_exp_f32_e32 v82, v82
	v_exp_f32_e32 v83, v83
	v_pk_mul_f32 v[66:67], v[130:131], v[66:67]
	v_pk_mul_f32 v[48:49], v[48:49], v[50:51]
	v_cndmask_b32_e64 v84, v105, v230, s[50:51]
	v_pk_mul_f32 v[50:51], v[82:83], v[52:53]
	v_cvt_pk_bf16_f32 v52, v66, v67
	v_add_u32_e32 v66, v160, v162
	ds_read_b64 v[66:67], v66
	v_cndmask_b32_e64 v85, v105, v230, s[52:53]
	v_mul_f32_e32 v84, v84, v253
	v_mul_f32_e32 v85, v85, v254
	v_exp_f32_e32 v84, v84
	v_exp_f32_e32 v85, v85
	v_cvt_pk_bf16_f32 v60, v48, v49
	v_cvt_pk_bf16_f32 v61, v50, v51
	v_pk_mul_f32 v[80:81], v[242:243], v[80:81]
	v_pk_mul_f32 v[54:55], v[84:85], v[54:55]
	v_cvt_pk_bf16_f32 v51, v80, v81
	v_cvt_pk_bf16_f32 v62, v54, v55
	v_cvt_pk_bf16_f32 v57, v88, v89
	v_pk_mul_f32 v[78:79], v[240:241], v[78:79]
	s_waitcnt lgkmcnt(0)
	v_mfma_f32_16x16x32_bf16 v[84:87], v[64:67], v[60:63], 0
	v_add_u32_e32 v64, v163, v164
	v_add_u32_e32 v66, v163, v165
	ds_read_b64 v[64:65], v64
	ds_read_b64 v[66:67], v66
	s_waitcnt lgkmcnt(0)
	v_mfma_f32_16x16x32_bf16 v[80:83], v[64:67], v[60:63], 0
	v_add_u32_e32 v64, v166, v167
	v_add_u32_e32 v66, v166, v168
	ds_read_b64 v[64:65], v64
	ds_read_b64 v[66:67], v66
	s_waitcnt lgkmcnt(0)
	v_mfma_f32_16x16x32_bf16 v[88:91], v[64:67], v[60:63], 0
	v_add_u32_e32 v64, v169, v170
	v_add_u32_e32 v66, v169, v171
	ds_read_b64 v[64:65], v64
	ds_read_b64 v[66:67], v66
	v_pk_mul_f32 v[76:77], v[238:239], v[76:77]
	v_cvt_pk_bf16_f32 v50, v78, v79
	v_cvt_pk_bf16_f32 v49, v76, v77
	s_waitcnt lgkmcnt(0)
	v_mfma_f32_16x16x32_bf16 v[76:79], v[64:67], v[60:63], 0
	v_add_u32_e32 v64, v172, v161
	v_add_u32_e32 v66, v172, v162
	ds_read_b64 v[64:65], v64
	ds_read_b64 v[66:67], v66
	v_pk_mul_f32 v[74:75], v[236:237], v[74:75]
	v_pk_mul_f32 v[72:73], v[234:235], v[72:73]
	v_cvt_pk_bf16_f32 v48, v74, v75
	v_cvt_pk_bf16_f32 v55, v72, v73
	s_waitcnt lgkmcnt(0)
	v_mfma_f32_16x16x32_bf16 v[72:75], v[64:67], v[60:63], 0
	v_add_u32_e32 v64, v173, v164
	v_add_u32_e32 v66, v173, v165
	ds_read_b64 v[64:65], v64
	ds_read_b64 v[66:67], v66
	v_pk_mul_f32 v[70:71], v[232:233], v[70:71]
	v_pk_mul_f32 v[68:69], v[132:133], v[68:69]
	v_cvt_pk_bf16_f32 v54, v70, v71
	v_cvt_pk_bf16_f32 v53, v68, v69
	s_waitcnt lgkmcnt(0)
	v_mfma_f32_16x16x32_bf16 v[68:71], v[64:67], v[60:63], 0
	v_add_u32_e32 v64, v174, v167
	v_add_u32_e32 v66, v174, v168
	ds_read_b64 v[64:65], v64
	ds_read_b64 v[66:67], v66
	s_waitcnt lgkmcnt(0)
	v_mfma_f32_16x16x32_bf16 v[64:67], v[64:67], v[60:63], 0
	v_mfma_f32_16x16x32_bf16 v[60:63], v[92:95], v[60:63], 0
	v_add_u32_e32 v92, v160, v176
	v_add_u32_e32 v94, v160, v177
	ds_read_b64 v[92:93], v92
	ds_read_b64 v[94:95], v94
	s_waitcnt lgkmcnt(0)
	v_mfma_f32_16x16x32_bf16 v[84:87], v[92:95], v[56:59], v[84:87]
	v_add_u32_e32 v92, v163, v178
	v_add_u32_e32 v94, v163, v179
	ds_read_b64 v[92:93], v92
	ds_read_b64 v[94:95], v94
	s_waitcnt lgkmcnt(0)
	v_mfma_f32_16x16x32_bf16 v[80:83], v[92:95], v[56:59], v[80:83]
	v_add_u32_e32 v92, v166, v180
	v_add_u32_e32 v94, v166, v181
	ds_read_b64 v[92:93], v92
	ds_read_b64 v[94:95], v94
	s_waitcnt lgkmcnt(0)
	v_mfma_f32_16x16x32_bf16 v[88:91], v[92:95], v[56:59], v[88:91]
	v_add_u32_e32 v92, v169, v182
	v_add_u32_e32 v94, v169, v183
	ds_read_b64 v[92:93], v92
	ds_read_b64 v[94:95], v94
	s_waitcnt lgkmcnt(0)
	v_mfma_f32_16x16x32_bf16 v[92:95], v[92:95], v[56:59], v[76:79]
	s_nop 2
	v_add_u32_e32 v76, v172, v176
	v_add_u32_e32 v78, v172, v177
	ds_read_b64 v[76:77], v76
	ds_read_b64 v[78:79], v78
	s_waitcnt lgkmcnt(0)
	v_mfma_f32_16x16x32_bf16 v[72:75], v[76:79], v[56:59], v[72:75]
	v_add_u32_e32 v76, v173, v178
	v_add_u32_e32 v78, v173, v179
	ds_read_b64 v[76:77], v76
	ds_read_b64 v[78:79], v78
	s_waitcnt lgkmcnt(0)
	v_mfma_f32_16x16x32_bf16 v[68:71], v[76:79], v[56:59], v[68:71]
	v_add_u32_e32 v76, v174, v180
	v_add_u32_e32 v78, v174, v181
	ds_read_b64 v[76:77], v76
	ds_read_b64 v[78:79], v78
	s_waitcnt lgkmcnt(0)
	v_mfma_f32_16x16x32_bf16 v[64:67], v[76:79], v[56:59], v[64:67]
	v_add_u32_e32 v76, v175, v182
	v_add_u32_e32 v78, v175, v183
	ds_read_b64 v[76:77], v76
	ds_read_b64 v[78:79], v78
	s_waitcnt lgkmcnt(0)
	v_mfma_f32_16x16x32_bf16 v[56:59], v[76:79], v[56:59], v[60:63]
	v_add_u32_e32 v76, v163, v186
	v_add_u32_e32 v78, v163, v187
	ds_read_b64 v[76:77], v76
	ds_read_b64 v[78:79], v78
	s_waitcnt lgkmcnt(0)
	v_mfma_f32_16x16x32_bf16 v[76:79], v[76:79], v[52:55], v[80:83]
	s_nop 2
	v_add_u32_e32 v80, v166, v188
	v_add_u32_e32 v82, v166, v189
	ds_read_b64 v[80:81], v80
	ds_read_b64 v[82:83], v82
	s_waitcnt lgkmcnt(0)
	v_mfma_f32_16x16x32_bf16 v[80:83], v[80:83], v[52:55], v[88:91]
	s_nop 2
	v_add_u32_e32 v88, v172, v184
	v_add_u32_e32 v90, v172, v185
	ds_read_b64 v[88:89], v88
	ds_read_b64 v[90:91], v90
	s_waitcnt lgkmcnt(0)
	v_mfma_f32_16x16x32_bf16 v[72:75], v[88:91], v[52:55], v[72:75]
	v_add_u32_e32 v88, v173, v186
	v_add_u32_e32 v90, v173, v187
	v_add_u32_e32 v60, v160, v184
	v_add_u32_e32 v62, v160, v185
	ds_read_b64 v[88:89], v88
	ds_read_b64 v[90:91], v90
	ds_read_b64 v[60:61], v60
	ds_read_b64 v[62:63], v62
	s_waitcnt lgkmcnt(2)
	v_mfma_f32_16x16x32_bf16 v[88:91], v[88:91], v[52:55], v[68:71]
	s_nop 2
	v_add_u32_e32 v68, v174, v188
	v_add_u32_e32 v70, v174, v189
	ds_read_b64 v[68:69], v68
	ds_read_b64 v[70:71], v70
	s_waitcnt lgkmcnt(2)
; #define LAS __attribute__((address_space(3)))
; #define MFMA16(a, b, c) __builtin_amdgcn_mfma_f32_16x16x32_bf16((a), (b), (c), 0, 0, 0)
; __device__ __forceinline__ void ret_unit(LAS unsigned char* lds, int u, const bf16* PROJ, const int* pos, const float* dec_f, const float* dec_b, const bf16* ST,
;                                          const float* gn_w, const float* gn_b, bf16* MIX, int tid, const WsRef& wsr) {
;     ...
;         for (int n = 0; n < 8; ++n) { const int sw = (2 * n + (fr >> 3)) & 7, jc = kk * 4 + (fq >> 1); const LAS bf16* vr = VT + (n * 16 + fr) * LDT + 4 * (fq & 1);
;             const u32x2 lo = *(const LAS u32x2*)(vr + ((jc ^ sw) << 3)), hi = *(const LAS u32x2*)(vr + (((jc + 2) ^ sw) << 3)); u32x4 w; w.x = lo.x; w.y = lo.y; w.z = hi.x; w.w = hi.y;
;             o[n] = MFMA16(__builtin_bit_cast(bf16x8, w), pf[kk], o[n]); }
;     __syncthreads();
; #pragma unroll
;     for (int i = 0; i < 4; ++i) { const int id = tid + 512 * i, e = id >> 4, dch = id & 15;
;         *(LAS u32x4*)(Ks + e * LDT + dch * 8) = sf[i]; *(LAS u32x4*)(VT + e * LDT + dch * 8) = sb[i]; }
;     __syncthreads();
;     {
;         f32x4 tf[8], tb[8];
; #pragma unroll
;         for (int n = 0; n < 8; ++n) { tf[n] = (f32x4){0.f, 0.f, 0.f, 0.f}; tb[n] = (f32x4){0.f, 0.f, 0.f, 0.f}; }
; #pragma unroll
;         for (int kk = 0; kk < 4; ++kk)
; #pragma unroll
;             for (int n = 0; n < 8; ++n) { const bf16x8 yf = *(const LAS bf16x8*)(Ks + (n * 16 + fr) * LDT + kk * 32 + fq * 8); const bf16x8 yb = *(const LAS bf16x8*)(VT + (n * 16 + fr) * LDT + kk * 32 + fq * 8);
;                 tf[n] = MFMA16(yf, qf[kk], tf[n]); tb[n] = MFMA16(yb, qf[kk], tb[n]); }
	v_mfma_f32_16x16x32_bf16 v[60:63], v[60:63], v[52:55], v[84:87]
	s_nop 2
	v_add_u32_e32 v84, v169, v190
	v_add_u32_e32 v86, v169, v191
	ds_read_b64 v[84:85], v84
	ds_read_b64 v[86:87], v86
	s_waitcnt lgkmcnt(0)
	v_mfma_f32_16x16x32_bf16 v[84:87], v[84:87], v[52:55], v[92:95]
	v_mfma_f32_16x16x32_bf16 v[92:95], v[68:71], v[52:55], v[64:67]
	v_add_u32_e32 v68, v172, v192
	v_add_u32_e32 v70, v172, v193
	ds_read_b64 v[68:69], v68
	ds_read_b64 v[70:71], v70
	v_add_u32_e32 v64, v175, v190
	v_add_u32_e32 v66, v175, v191
	ds_read_b64 v[64:65], v64
	ds_read_b64 v[66:67], v66
	s_waitcnt lgkmcnt(0)
	v_mfma_f32_16x16x32_bf16 v[232:235], v[64:67], v[52:55], v[56:59]
	v_add_u32_e32 v52, v160, v192
	v_add_u32_e32 v54, v160, v193
	ds_read_b64 v[52:53], v52
	ds_read_b64 v[54:55], v54
	v_add_u32_e32 v56, v163, v194
	v_add_u32_e32 v58, v163, v195
	ds_read_b64 v[56:57], v56
	ds_read_b64 v[58:59], v58
	s_waitcnt lgkmcnt(2)
	v_mfma_f32_16x16x32_bf16 v[52:55], v[52:55], v[48:51], v[60:63]
	s_nop 2
	v_add_u32_e32 v60, v166, v196
	v_add_u32_e32 v62, v166, v197
	ds_read_b64 v[60:61], v60
	ds_read_b64 v[62:63], v62
	v_add_u32_e32 v64, v169, v198
	v_add_u32_e32 v66, v169, v199
	s_waitcnt lgkmcnt(2)
	v_mfma_f32_16x16x32_bf16 v[56:59], v[56:59], v[48:51], v[76:79]
	ds_read_b64 v[64:65], v64
	ds_read_b64 v[66:67], v66
	s_waitcnt lgkmcnt(2)
	v_mfma_f32_16x16x32_bf16 v[60:63], v[60:63], v[48:51], v[80:83]
	v_add_u32_e32 v76, v174, v196
	v_add_u32_e32 v78, v174, v197
	s_nop 0
	v_add_u32_e32 v80, v175, v198
	v_mfma_f32_16x16x32_bf16 v[68:71], v[68:71], v[48:51], v[72:75]
	v_add_u32_e32 v82, v175, v199
	ds_read_b64 v[76:77], v76
	ds_read_b64 v[78:79], v78
	v_add_u32_e32 v72, v173, v194
	v_add_u32_e32 v74, v173, v195
	ds_read_b64 v[72:73], v72
	ds_read_b64 v[74:75], v74
	ds_read_b64 v[80:81], v80
	ds_read_b64 v[82:83], v82
	s_waitcnt lgkmcnt(0)
	s_barrier
	ds_write_b128 v200, v[4:7] offset:34816
	ds_write_b128 v201, v[12:15]
	ds_write_b128 v202, v[8:11] offset:34816
	ds_write_b128 v203, v[16:19]
	ds_write_b128 v205, v[24:27] offset:34816
	ds_write_b128 v206, v[20:23]
	ds_write_b128 v207, v[32:35] offset:34816
	ds_write_b128 v208, v[36:39]
	s_waitcnt lgkmcnt(0)
	s_barrier
	ds_read_b128 v[4:7], v209 offset:34816
	ds_read_b128 v[8:11], v210
	s_waitcnt lgkmcnt(1)
	v_mfma_f32_16x16x32_bf16 v[12:15], v[4:7], v[44:47], 0
	s_waitcnt lgkmcnt(0)
	v_mfma_f32_16x16x32_bf16 v[16:19], v[8:11], v[44:47], 0
	ds_read_b128 v[4:7], v209 offset:39168
	ds_read_b128 v[8:11], v211
	s_waitcnt lgkmcnt(1)
	v_mfma_f32_16x16x32_bf16 v[32:35], v[4:7], v[44:47], 0
	s_waitcnt lgkmcnt(0)
	v_mfma_f32_16x16x32_bf16 v[36:39], v[8:11], v[44:47], 0
	ds_read_b128 v[4:7], v209 offset:43520
	ds_read_b128 v[8:11], v212
	v_mfma_f32_16x16x32_bf16 v[72:75], v[72:75], v[48:51], v[88:91]
	v_mfma_f32_16x16x32_bf16 v[76:79], v[76:79], v[48:51], v[92:95]
	s_waitcnt lgkmcnt(1)
	v_mfma_f32_16x16x32_bf16 v[88:91], v[4:7], v[44:47], 0
	s_waitcnt lgkmcnt(0)
	v_mfma_f32_16x16x32_bf16 v[92:95], v[8:11], v[44:47], 0
	ds_read_b128 v[4:7], v209 offset:47872
	ds_read_b128 v[8:11], v213
	v_mfma_f32_16x16x32_bf16 v[64:67], v[64:67], v[48:51], v[84:87]
	v_mfma_f32_16x16x32_bf16 v[48:51], v[80:83], v[48:51], v[232:235]
	s_waitcnt lgkmcnt(1)
	v_mfma_f32_16x16x32_bf16 v[232:235], v[4:7], v[44:47], 0
	s_waitcnt lgkmcnt(0)
	v_mfma_f32_16x16x32_bf16 v[236:239], v[8:11], v[44:47], 0
	ds_read_b128 v[4:7], v209 offset:52224
	ds_read_b128 v[8:11], v214
	s_waitcnt lgkmcnt(1)
	v_mfma_f32_16x16x32_bf16 v[240:243], v[4:7], v[44:47], 0
	s_waitcnt lgkmcnt(0)
	v_mfma_f32_16x16x32_bf16 v[244:247], v[8:11], v[44:47], 0
	ds_read_b128 v[4:7], v209 offset:56576
	ds_read_b128 v[8:11], v215
	s_waitcnt lgkmcnt(1)
	v_mfma_f32_16x16x32_bf16 v[80:83], v[4:7], v[44:47], 0
	s_waitcnt lgkmcnt(0)
	v_mfma_f32_16x16x32_bf16 v[84:87], v[8:11], v[44:47], 0
	ds_read_b128 v[4:7], v209 offset:60928
	ds_read_b128 v[8:11], v216
	s_waitcnt lgkmcnt(1)
	v_mfma_f32_16x16x32_bf16 v[20:23], v[4:7], v[44:47], 0
	ds_read_b128 v[4:7], v209 offset:65280
	ds_read_b128 v[248:251], v217
	s_waitcnt lgkmcnt(2)
	v_mfma_f32_16x16x32_bf16 v[24:27], v[8:11], v[44:47], 0
	s_waitcnt lgkmcnt(1)
	v_mfma_f32_16x16x32_bf16 v[8:11], v[4:7], v[44:47], 0
	s_waitcnt lgkmcnt(0)
	v_mfma_f32_16x16x32_bf16 v[4:7], v[248:251], v[44:47], 0
	ds_read_b128 v[44:47], v209 offset:34880
	ds_read_b128 v[248:251], v210 offset:64
	s_waitcnt lgkmcnt(1)
	v_mfma_f32_16x16x32_bf16 v[12:15], v[44:47], v[40:43], v[12:15]
	s_waitcnt lgkmcnt(0)
	v_mfma_f32_16x16x32_bf16 v[16:19], v[248:251], v[40:43], v[16:19]
	ds_read_b128 v[44:47], v209 offset:39232
	ds_read_b128 v[248:251], v211 offset:64
	s_waitcnt lgkmcnt(1)
	v_mfma_f32_16x16x32_bf16 v[32:35], v[44:47], v[40:43], v[32:35]
	s_waitcnt lgkmcnt(0)
	v_mfma_f32_16x16x32_bf16 v[36:39], v[248:251], v[40:43], v[36:39]
	ds_read_b128 v[44:47], v209 offset:43584
	ds_read_b128 v[248:251], v212 offset:64
	s_waitcnt lgkmcnt(1)
	v_mfma_f32_16x16x32_bf16 v[44:47], v[44:47], v[40:43], v[88:91]
	s_waitcnt lgkmcnt(0)
	v_mfma_f32_16x16x32_bf16 v[88:91], v[248:251], v[40:43], v[92:95]
	s_nop 2
	ds_read_b128 v[92:95], v209 offset:47936
	ds_read_b128 v[248:251], v213 offset:64
	s_waitcnt lgkmcnt(1)
	v_mfma_f32_16x16x32_bf16 v[92:95], v[92:95], v[40:43], v[232:235]
	s_waitcnt lgkmcnt(0)
	v_mfma_f32_16x16x32_bf16 v[232:235], v[248:251], v[40:43], v[236:239]
	s_nop 2
	ds_read_b128 v[236:239], v209 offset:52288
	ds_read_b128 v[248:251], v214 offset:64
	s_waitcnt lgkmcnt(1)
	v_mfma_f32_16x16x32_bf16 v[236:239], v[236:239], v[40:43], v[240:243]
	s_waitcnt lgkmcnt(0)
	v_mfma_f32_16x16x32_bf16 v[240:243], v[248:251], v[40:43], v[244:247]
	s_nop 2
	ds_read_b128 v[244:247], v209 offset:56640
	ds_read_b128 v[248:251], v215 offset:64
	s_waitcnt lgkmcnt(1)
; #define LAS __attribute__((address_space(3)))
; #define MFMA16(a, b, c) __builtin_amdgcn_mfma_f32_16x16x32_bf16((a), (b), (c), 0, 0, 0)
; __device__ __forceinline__ void ret_unit(LAS unsigned char* lds, int u, const bf16* PROJ, const int* pos, const float* dec_f, const float* dec_b, const bf16* ST,
;                                          const float* gn_w, const float* gn_b, bf16* MIX, int tid, const WsRef& wsr) {
;     ...
; #pragma unroll
;         for (int kk = 0; kk < 4; ++kk)
; #pragma unroll
;             for (int n = 0; n < 8; ++n) { const bf16x8 yf = *(const LAS bf16x8*)(Ks + (n * 16 + fr) * LDT + kk * 32 + fq * 8); const bf16x8 yb = *(const LAS bf16x8*)(VT + (n * 16 + fr) * LDT + kk * 32 + fq * 8);
;                 tf[n] = MFMA16(yf, qf[kk], tf[n]); tb[n] = MFMA16(yb, qf[kk], tb[n]); }
	v_mfma_f32_16x16x32_bf16 v[80:83], v[244:247], v[40:43], v[80:83]
	s_waitcnt lgkmcnt(0)
	v_mfma_f32_16x16x32_bf16 v[84:87], v[248:251], v[40:43], v[84:87]
	ds_read_b128 v[244:247], v209 offset:60992
	ds_read_b128 v[248:251], v216 offset:64
	s_waitcnt lgkmcnt(1)
	v_mfma_f32_16x16x32_bf16 v[244:247], v[244:247], v[40:43], v[20:23]
	s_waitcnt lgkmcnt(0)
	v_mfma_f32_16x16x32_bf16 v[248:251], v[248:251], v[40:43], v[24:27]
	s_nop 0
	ds_read_b128 v[20:23], v209 offset:65344
	s_nop 0
	ds_read_b128 v[24:27], v217 offset:64
	s_waitcnt lgkmcnt(1)
	v_mfma_f32_16x16x32_bf16 v[8:11], v[20:23], v[40:43], v[8:11]
	s_waitcnt lgkmcnt(0)
	v_mfma_f32_16x16x32_bf16 v[4:7], v[24:27], v[40:43], v[4:7]
	ds_read_b128 v[20:23], v209 offset:34944
	ds_read_b128 v[24:27], v210 offset:128
	s_waitcnt lgkmcnt(1)
	v_mfma_f32_16x16x32_bf16 v[40:43], v[20:23], v[28:31], v[12:15]
	s_waitcnt lgkmcnt(0)
	v_mfma_f32_16x16x32_bf16 v[130:133], v[24:27], v[28:31], v[16:19]
	s_nop 0
	ds_read_b128 v[12:15], v209 offset:39296
	s_nop 0
	ds_read_b128 v[16:19], v211 offset:128
	s_waitcnt lgkmcnt(1)
	v_mfma_f32_16x16x32_bf16 v[32:35], v[12:15], v[28:31], v[32:35]
	s_waitcnt lgkmcnt(0)
	v_mfma_f32_16x16x32_bf16 v[36:39], v[16:19], v[28:31], v[36:39]
	ds_read_b128 v[12:15], v209 offset:43648
	ds_read_b128 v[16:19], v212 offset:128
	s_waitcnt lgkmcnt(1)
	v_mfma_f32_16x16x32_bf16 v[44:47], v[12:15], v[28:31], v[44:47]
	s_waitcnt lgkmcnt(0)
	v_mfma_f32_16x16x32_bf16 v[88:91], v[16:19], v[28:31], v[88:91]
	ds_read_b128 v[12:15], v209 offset:48000
	ds_read_b128 v[16:19], v213 offset:128
	s_waitcnt lgkmcnt(1)
	v_mfma_f32_16x16x32_bf16 v[92:95], v[12:15], v[28:31], v[92:95]
	s_waitcnt lgkmcnt(0)
	v_mfma_f32_16x16x32_bf16 v[232:235], v[16:19], v[28:31], v[232:235]
	ds_read_b128 v[12:15], v209 offset:52352
	ds_read_b128 v[16:19], v214 offset:128
	s_waitcnt lgkmcnt(1)
	v_mfma_f32_16x16x32_bf16 v[236:239], v[12:15], v[28:31], v[236:239]
	s_waitcnt lgkmcnt(0)
	v_mfma_f32_16x16x32_bf16 v[240:243], v[16:19], v[28:31], v[240:243]
	ds_read_b128 v[12:15], v209 offset:56704
	ds_read_b128 v[16:19], v215 offset:128
	s_waitcnt lgkmcnt(1)
	v_mfma_f32_16x16x32_bf16 v[20:23], v[12:15], v[28:31], v[80:83]
	s_waitcnt lgkmcnt(0)
	v_mfma_f32_16x16x32_bf16 v[24:27], v[16:19], v[28:31], v[84:87]
	ds_read_b128 v[12:15], v209 offset:61056
	ds_read_b128 v[16:19], v216 offset:128
	ds_read_b128 v[80:83], v209 offset:65408
	ds_read_b128 v[84:87], v217 offset:128
	s_waitcnt lgkmcnt(3)
	v_mfma_f32_16x16x32_bf16 v[12:15], v[12:15], v[28:31], v[244:247]
	s_waitcnt lgkmcnt(2)
	v_mfma_f32_16x16x32_bf16 v[16:19], v[16:19], v[28:31], v[248:251]
	s_waitcnt lgkmcnt(1)
	v_mfma_f32_16x16x32_bf16 v[8:11], v[80:83], v[28:31], v[8:11]
	s_waitcnt lgkmcnt(0)
	v_mfma_f32_16x16x32_bf16 v[4:7], v[84:87], v[28:31], v[4:7]
	ds_read_b128 v[28:31], v209 offset:35008
	ds_read_b128 v[80:83], v210 offset:192
	s_waitcnt lgkmcnt(1)
	v_mfma_f32_16x16x32_bf16 v[28:31], v[28:31], v[0:3], v[40:43]
	s_waitcnt lgkmcnt(0)
	v_mfma_f32_16x16x32_bf16 v[40:43], v[80:83], v[0:3], v[130:133]
	ds_read_b128 v[80:83], v209 offset:39360
	ds_read_b128 v[84:87], v211 offset:192
	s_waitcnt lgkmcnt(1)
	v_mfma_f32_16x16x32_bf16 v[80:83], v[80:83], v[0:3], v[32:35]
	s_waitcnt lgkmcnt(0)
	v_mfma_f32_16x16x32_bf16 v[34:37], v[84:87], v[0:3], v[36:39]
	ds_read_b128 v[84:87], v209 offset:43712
	ds_read_b128 v[130:133], v212 offset:192
	s_waitcnt lgkmcnt(1)
	v_mfma_f32_16x16x32_bf16 v[44:47], v[84:87], v[0:3], v[44:47]
	s_waitcnt lgkmcnt(0)
	v_mfma_f32_16x16x32_bf16 v[84:87], v[130:133], v[0:3], v[88:91]
	s_nop 2
	ds_read_b128 v[88:91], v209 offset:48064
	ds_read_b128 v[130:133], v213 offset:192
	s_waitcnt lgkmcnt(1)
	v_mfma_f32_16x16x32_bf16 v[88:91], v[88:91], v[0:3], v[92:95]
	s_waitcnt lgkmcnt(0)
	v_mfma_f32_16x16x32_bf16 v[92:95], v[130:133], v[0:3], v[232:235]
	ds_read_b128 v[130:133], v209 offset:52416
	s_nop 1
	ds_read_b128 v[232:235], v214 offset:192
	s_waitcnt lgkmcnt(1)
	v_mfma_f32_16x16x32_bf16 v[130:133], v[130:133], v[0:3], v[236:239]
	s_waitcnt lgkmcnt(0)
	v_mfma_f32_16x16x32_bf16 v[232:235], v[232:235], v[0:3], v[240:243]
	s_nop 0
	ds_read_b128 v[236:239], v209 offset:56768
	s_nop 0
	ds_read_b128 v[240:243], v215 offset:192
	s_waitcnt lgkmcnt(1)
	v_mfma_f32_16x16x32_bf16 v[236:239], v[236:239], v[0:3], v[20:23]
	s_waitcnt lgkmcnt(0)
	v_mfma_f32_16x16x32_bf16 v[240:243], v[240:243], v[0:3], v[24:27]
	s_nop 0
	ds_read_b128 v[20:23], v209 offset:61120
	s_nop 0
	ds_read_b128 v[24:27], v216 offset:192
	s_waitcnt lgkmcnt(1)
	v_mfma_f32_16x16x32_bf16 v[12:15], v[20:23], v[0:3], v[12:15]
	s_waitcnt lgkmcnt(0)
	v_mfma_f32_16x16x32_bf16 v[244:247], v[24:27], v[0:3], v[16:19]
	s_nop 2
	ds_read_b128 v[16:19], v209 offset:65472
	ds_read_b128 v[20:23], v217 offset:192
	s_waitcnt lgkmcnt(1)
	v_mfma_f32_16x16x32_bf16 v[8:11], v[16:19], v[0:3], v[8:11]
	s_waitcnt lgkmcnt(0)
; __device__ __forceinline__ float fexp2(float x) { return __builtin_amdgcn_exp2f(x); }
; __device__ __forceinline__ void ret_unit(LAS unsigned char* lds, int u, const bf16* PROJ, const int* pos, const float* dec_f, const float* dec_b, const bf16* ST,
;                                          const float* gn_w, const float* gn_b, bf16* MIX, int tid, const WsRef& wsr) {
;     ...
;         const float xif = fexp2(lgf2 * (float)(q + 1)), xib = fexp2(lgb2 * (float)(128 - q));
; #pragma unroll
;         for (int n = 0; n < 8; ++n) o[n] = o[n] + tf[n] * xif + tb[n] * xib;
;     }
;     float sm = 0.f;
; #pragma unroll
;     for (int n = 0; n < 8; ++n) sm += (o[n][0] + o[n][1]) + (o[n][2] + o[n][3]);
;     sm += __shfl_xor(sm, 16); sm += __shfl_xor(sm, 32);
;     const float mu = sm * (1.f / 128.f);
;     float vq = 0.f;
; #pragma unroll
;     for (int n = 0; n < 8; ++n) { const f32x4 d = o[n] - mu; vq += (d[0] * d[0] + d[1] * d[1]) + (d[2] * d[2] + d[3] * d[3]); }
;     vq += __shfl_xor(vq, 16); vq += __shfl_xor(vq, 32);
	v_mfma_f32_16x16x32_bf16 v[248:251], v[20:23], v[0:3], v[4:7]
	v_mul_f32_e32 v0, v105, v218
	v_exp_f32_e32 v38, v0
	v_mul_f32_e32 v0, v230, v219
	v_exp_f32_e32 v230, v0
	v_pk_fma_f32 v[2:3], v[38:39], v[28:29], v[52:53] op_sel_hi:[0,1,1]
	v_pk_fma_f32 v[16:17], v[38:39], v[132:133], v[70:71] op_sel_hi:[0,1,1]
	v_pk_fma_f32 v[0:1], v[38:39], v[30:31], v[54:55] op_sel_hi:[0,1,1]
	v_pk_fma_f32 v[32:33], v[230:231], v[40:41], v[2:3] op_sel_hi:[0,1,1]
	v_pk_fma_f32 v[2:3], v[38:39], v[80:81], v[56:57] op_sel_hi:[0,1,1]
	v_pk_fma_f32 v[18:19], v[38:39], v[130:131], v[68:69] op_sel_hi:[0,1,1]
	v_pk_fma_f32 v[22:23], v[230:231], v[234:235], v[16:17] op_sel_hi:[0,1,1]
	v_pk_fma_f32 v[16:17], v[38:39], v[238:239], v[74:75] op_sel_hi:[0,1,1]
	v_pk_fma_f32 v[12:13], v[38:39], v[12:13], v[76:77] op_sel_hi:[0,1,1]
	v_pk_fma_f32 v[30:31], v[230:231], v[42:43], v[0:1] op_sel_hi:[0,1,1]
	v_pk_fma_f32 v[0:1], v[38:39], v[82:83], v[58:59] op_sel_hi:[0,1,1]
	v_pk_fma_f32 v[28:29], v[230:231], v[34:35], v[2:3] op_sel_hi:[0,1,1]
	v_pk_fma_f32 v[24:25], v[230:231], v[232:233], v[18:19] op_sel_hi:[0,1,1]
	v_pk_fma_f32 v[18:19], v[230:231], v[242:243], v[16:17] op_sel_hi:[0,1,1]
	v_pk_fma_f32 v[16:17], v[230:231], v[244:245], v[12:13] op_sel_hi:[0,1,1]
	v_pk_fma_f32 v[10:11], v[38:39], v[10:11], v[50:51] op_sel_hi:[0,1,1]
	v_pk_fma_f32 v[12:13], v[38:39], v[8:9], v[48:49] op_sel_hi:[0,1,1]
	v_pk_fma_f32 v[26:27], v[230:231], v[36:37], v[0:1] op_sel_hi:[0,1,1]
	v_pk_fma_f32 v[8:9], v[230:231], v[250:251], v[10:11] op_sel_hi:[0,1,1]
	v_pk_fma_f32 v[10:11], v[230:231], v[248:249], v[12:13] op_sel_hi:[0,1,1]
	v_mov_b32_e32 v12, v32
	v_mov_b32_e32 v13, v28
	v_mov_b32_e32 v34, v33
	v_mov_b32_e32 v35, v29
	v_pk_fma_f32 v[0:1], v[38:39], v[46:47], v[62:63] op_sel_hi:[0,1,1]
	v_pk_fma_f32 v[2:3], v[38:39], v[44:45], v[60:61] op_sel_hi:[0,1,1]
	v_pk_add_f32 v[12:13], v[12:13], v[34:35]
	v_mov_b32_e32 v34, v30
	v_mov_b32_e32 v35, v26
	v_mov_b32_e32 v36, v31
	v_mov_b32_e32 v37, v27
	v_pk_fma_f32 v[4:5], v[230:231], v[86:87], v[0:1] op_sel_hi:[0,1,1]
	v_pk_fma_f32 v[6:7], v[230:231], v[84:85], v[2:3] op_sel_hi:[0,1,1]
	v_pk_add_f32 v[34:35], v[34:35], v[36:37]
	v_mov_b32_e32 v36, v6
	v_pk_add_f32 v[12:13], v[12:13], v[34:35]
	v_pk_mov_b32 v[34:35], v[6:7], v[4:5] op_sel:[1,0]
	v_mov_b32_e32 v37, v5
	v_pk_fma_f32 v[0:1], v[38:39], v[90:91], v[66:67] op_sel_hi:[0,1,1]
	v_pk_fma_f32 v[2:3], v[38:39], v[88:89], v[64:65] op_sel_hi:[0,1,1]
	v_pk_add_f32 v[34:35], v[34:35], v[36:37]
	v_pk_fma_f32 v[0:1], v[230:231], v[94:95], v[0:1] op_sel_hi:[0,1,1]
	v_pk_fma_f32 v[2:3], v[230:231], v[92:93], v[2:3] op_sel_hi:[0,1,1]
	v_add_f32_e32 v12, 0, v12
	v_pk_add_f32 v[34:35], v[34:35], v[34:35] op_sel:[0,1] op_sel_hi:[1,0]
	v_pk_fma_f32 v[20:21], v[38:39], v[236:237], v[72:73] op_sel_hi:[0,1,1]
	v_pk_fma_f32 v[14:15], v[38:39], v[14:15], v[78:79] op_sel_hi:[0,1,1]
	v_add_f32_e32 v12, v12, v13
	v_add_f32_e32 v36, v2, v3
	v_add_f32_e32 v38, v0, v1
	v_mov_b32_e32 v13, v24
	v_mov_b32_e32 v35, v25
	v_mov_b32_e32 v37, v22
	v_mov_b32_e32 v39, v23
	v_pk_fma_f32 v[20:21], v[230:231], v[240:241], v[20:21] op_sel_hi:[0,1,1]
	v_pk_add_f32 v[12:13], v[12:13], v[34:35]
	v_pk_add_f32 v[34:35], v[36:37], v[38:39]
	v_mov_b32_e32 v36, v20
	v_pk_add_f32 v[12:13], v[12:13], v[34:35]
	v_pk_mov_b32 v[34:35], v[20:21], v[18:19] op_sel:[1,0]
	v_mov_b32_e32 v37, v19
	v_pk_add_f32 v[34:35], v[34:35], v[36:37]
	v_pk_fma_f32 v[14:15], v[230:231], v[246:247], v[14:15] op_sel_hi:[0,1,1]
	v_pk_add_f32 v[12:13], v[12:13], v[12:13] op_sel:[0,1] op_sel_hi:[1,0]
	v_pk_add_f32 v[34:35], v[34:35], v[34:35] op_sel:[0,1] op_sel_hi:[1,0]
	v_add_f32_e32 v36, v16, v17
	v_add_f32_e32 v38, v14, v15
	v_mov_b32_e32 v13, v10
	v_mov_b32_e32 v35, v11
	v_mov_b32_e32 v37, v8
	v_mov_b32_e32 v39, v9
	v_pk_add_f32 v[12:13], v[12:13], v[34:35]
	v_pk_add_f32 v[34:35], v[36:37], v[38:39]
	v_or_b32_e32 v48, s0, v126
	v_pk_add_f32 v[12:13], v[12:13], v[34:35]
	v_mov_b32_e32 v49, v97
	v_add_f32_e32 v12, v12, v13
	ds_bpermute_b32 v13, v220, v12
	s_waitcnt lgkmcnt(0)
	v_add_f32_e32 v12, v12, v13
	ds_bpermute_b32 v13, v221, v12
	s_waitcnt lgkmcnt(0)
	v_add_f32_e32 v40, v12, v13
	v_fmamk_f32 v33, v40, 0xbc000000, v33
	v_fmamk_f32 v29, v40, 0xbc000000, v29
	v_fmamk_f32 v31, v40, 0xbc000000, v31
	v_fmac_f32_e32 v32, 0xbc000000, v40
	v_fmamk_f32 v27, v40, 0xbc000000, v27
	v_fmac_f32_e32 v28, 0xbc000000, v40
	v_mov_b32_e32 v34, v33
	v_mov_b32_e32 v35, v29
	v_fmac_f32_e32 v30, 0xbc000000, v40
	v_fmac_f32_e32 v26, 0xbc000000, v40
	v_mov_b32_e32 v12, v32
	v_mov_b32_e32 v13, v28
	v_pk_mul_f32 v[34:35], v[34:35], v[34:35]
	v_mov_b32_e32 v36, v31
	v_mov_b32_e32 v37, v27
	v_pk_fma_f32 v[12:13], v[12:13], v[12:13], v[34:35]
	v_mov_b32_e32 v34, v30
	v_mov_b32_e32 v35, v26
	v_pk_mul_f32 v[36:37], v[36:37], v[36:37]
	v_fmamk_f32 v7, v40, 0xbc000000, v7
	v_pk_fma_f32 v[34:35], v[34:35], v[34:35], v[36:37]
	v_fmac_f32_e32 v6, 0xbc000000, v40
	v_pk_add_f32 v[12:13], v[12:13], v[34:35]
	v_fmamk_f32 v5, v40, 0xbc000000, v5
	v_fmac_f32_e32 v4, 0xbc000000, v40
	v_pk_add_f32 v[12:13], v[12:13], v[12:13] op_sel_hi:[0,1]
	v_pk_mul_f32 v[34:35], v[4:5], v[4:5]
	v_pk_mul_f32 v[36:37], v[6:7], v[6:7]
	v_fmac_f32_e32 v2, 0xbc000000, v40
	v_pk_mov_b32 v[38:39], v[36:37], v[34:35] op_sel:[1,0]
	v_mov_b32_e32 v37, v35
	v_fmamk_f32 v3, v40, 0xbc000000, v3
	v_fmac_f32_e32 v0, 0xbc000000, v40
	v_mul_f32_e32 v12, v2, v2
	v_pk_add_f32 v[34:35], v[38:39], v[36:37]
	v_fmamk_f32 v1, v40, 0xbc000000, v1
	v_pk_fma_f32 v[36:37], v[2:3], v[2:3], v[12:13] op_sel_hi:[1,1,0]
	v_mul_f32_e32 v12, v0, v0
	v_pk_add_f32 v[34:35], v[34:35], v[34:35] op_sel_hi:[0,1]
	v_pk_fma_f32 v[38:39], v[0:1], v[0:1], v[12:13] op_sel_hi:[1,1,0]
; __device__ __forceinline__ unsigned pk2(float lo, float hi) { return pg8::cvt_pk_bf16(lo, hi); }
; __device__ __forceinline__ float bflo(unsigned w) { return __uint_as_float(w << 16); }
; __device__ __forceinline__ float bfhi(unsigned w) { return __uint_as_float(w & 0xffff0000u); }
; __device__ __forceinline__ void ret_unit(LAS unsigned char* lds, int u, const bf16* PROJ, const int* pos, const float* dec_f, const float* dec_b, const bf16* ST,
;                                          const float* gn_w, const float* gn_b, bf16* MIX, int tid, const WsRef& wsr) {
;     ...
;     vq += __shfl_xor(vq, 16); vq += __shfl_xor(vq, 32);
;     const float rstd = rsqrtf(vq * (1.f / 128.f) + EPS);
;     const size_t row = row0 + q;
; #pragma unroll
;     for (int n = 0; n < 8; ++n) { const int col = h * 128 + n * 16 + 4 * fq;
;         const f32x4 gw = *(const f32x4*)(gn_w + col), gb = *(const f32x4*)(gn_b + col);
;         const u32x2 gg = *(const u32x2*)(PROJ + row * INC + 1536 + col);
;         const f32x4 g = (f32x4){bflo(gg.x), bfhi(gg.x), bflo(gg.y), bfhi(gg.y)};
;         f32x4 y = (o[n] - mu) * rstd * gw + gb;
; #pragma unroll
;         for (int r = 0; r < 4; ++r) y[r] = y[r] * g[r] * __builtin_amdgcn_rcpf(1.f + __expf(-g[r]));
;         u32x2 w; w.x = pk2(y[0], y[1]); w.y = pk2(y[2], y[3]); *(u32x2*)(MIX + row * D + col) = w; }
	v_fmamk_f32 v23, v40, 0xbc000000, v23
	v_fmac_f32_e32 v22, 0xbc000000, v40
	v_fmamk_f32 v25, v40, 0xbc000000, v25
	v_fmac_f32_e32 v24, 0xbc000000, v40
	v_mul_f32_e32 v36, v24, v24
	v_mul_f32_e32 v38, v25, v25
	v_mul_f32_e32 v34, v22, v22
	v_mul_f32_e32 v12, v23, v23
	v_pk_add_f32 v[36:37], v[36:37], v[38:39]
	v_pk_add_f32 v[12:13], v[34:35], v[12:13]
	v_fmamk_f32 v21, v40, 0xbc000000, v21
	v_pk_add_f32 v[12:13], v[36:37], v[12:13]
	v_fmac_f32_e32 v20, 0xbc000000, v40
	v_fmamk_f32 v19, v40, 0xbc000000, v19
	v_fmac_f32_e32 v18, 0xbc000000, v40
	v_pk_add_f32 v[12:13], v[12:13], v[12:13] op_sel_hi:[0,1]
	v_pk_mul_f32 v[34:35], v[18:19], v[18:19]
	v_pk_mul_f32 v[36:37], v[20:21], v[20:21]
	v_fmac_f32_e32 v16, 0xbc000000, v40
	v_pk_mov_b32 v[38:39], v[36:37], v[34:35] op_sel:[1,0]
	v_mov_b32_e32 v37, v35
	v_fmamk_f32 v17, v40, 0xbc000000, v17
	v_fmac_f32_e32 v14, 0xbc000000, v40
	v_mul_f32_e32 v12, v16, v16
	v_pk_add_f32 v[34:35], v[38:39], v[36:37]
	v_fmamk_f32 v15, v40, 0xbc000000, v15
	v_pk_fma_f32 v[36:37], v[16:17], v[16:17], v[12:13] op_sel_hi:[1,1,0]
	v_mul_f32_e32 v12, v14, v14
	v_pk_add_f32 v[34:35], v[34:35], v[34:35] op_sel_hi:[0,1]
	v_pk_fma_f32 v[38:39], v[14:15], v[14:15], v[12:13] op_sel_hi:[1,1,0]
	v_fmamk_f32 v9, v40, 0xbc000000, v9
	v_fmac_f32_e32 v8, 0xbc000000, v40
	v_fmamk_f32 v11, v40, 0xbc000000, v11
	v_fmac_f32_e32 v10, 0xbc000000, v40
	v_mul_f32_e32 v36, v10, v10
	v_mul_f32_e32 v38, v11, v11
	v_mul_f32_e32 v34, v8, v8
	v_mul_f32_e32 v12, v9, v9
	v_pk_add_f32 v[36:37], v[36:37], v[38:39]
	v_pk_add_f32 v[12:13], v[34:35], v[12:13]
	v_lshl_add_u64 v[34:35], s[4:5], 0, v[102:103]
	v_pk_add_f32 v[12:13], v[36:37], v[12:13]
	v_mov_b64_e32 v[36:37], s[6:7]
	v_add_f32_e32 v12, v12, v13
	ds_bpermute_b32 v13, v220, v12
	s_waitcnt lgkmcnt(0)
	v_add_f32_e32 v12, v12, v13
	ds_bpermute_b32 v13, v221, v12
	s_waitcnt lgkmcnt(0)
	v_add_f32_e32 v12, v12, v13
	v_fmamk_f32 v12, v12, 0x3c000000, v227
	v_cmp_gt_f32_e64 s[68:69], s1, v12
	v_mul_f32_e32 v13, 0x4b800000, v12
	v_mad_u64_u32 v[44:45], s[0:1], v34, s72, v[36:37]
	v_cndmask_b32_e64 v12, v12, v13, s[68:69]
	v_rsq_f32_e32 v12, v12
	v_mad_i32_i24 v45, v35, s72, v45
	v_lshlrev_b64 v[34:35], 11, v[34:35]
	v_lshl_add_u64 v[46:47], s[70:71], 0, v[34:35]
	v_mul_f32_e32 v13, 0x45800000, v12
	v_cndmask_b32_e64 v12, v12, v13, s[68:69]
	v_lshlrev_b32_e32 v13, 2, v48
	v_lshlrev_b32_e32 v48, 1, v48
	v_lshl_add_u64 v[34:35], v[44:45], 0, v[48:49]
	v_lshl_add_u64 v[46:47], v[46:47], 0, v[48:49]
	global_load_dwordx2 v[56:57], v[34:35], off offset:3072
	global_load_dwordx2 v[58:59], v[34:35], off offset:3104
	global_load_dwordx2 v[60:61], v[34:35], off offset:3136
	global_load_dwordx2 v[62:63], v[34:35], off offset:3168
	global_load_dwordx2 v[64:65], v[34:35], off offset:3200
	global_load_dwordx2 v[66:67], v[34:35], off offset:3232
	global_load_dwordx2 v[68:69], v[34:35], off offset:3264
	global_load_dwordx2 v[70:71], v[34:35], off offset:3296
	global_load_dwordx4 v[72:75], v13, s[22:23]
	global_load_dwordx4 v[76:79], v13, s[36:37]
	global_load_dwordx4 v[80:83], v13, s[22:23] offset:64
	global_load_dwordx4 v[84:87], v13, s[36:37] offset:64
	global_load_dwordx4 v[88:91], v13, s[22:23] offset:128
	global_load_dwordx4 v[92:95], v13, s[36:37] offset:128
	global_load_dwordx4 v[36:39], v13, s[22:23] offset:192
	global_load_dwordx4 v[40:43], v13, s[36:37] offset:192
	global_load_dwordx4 v[232:235], v13, s[22:23] offset:256
	global_load_dwordx4 v[236:239], v13, s[36:37] offset:256
	global_load_dwordx4 v[240:243], v13, s[22:23] offset:320
	global_load_dwordx4 v[248:251], v13, s[36:37] offset:320
	v_pk_mul_f32 v[32:33], v[32:33], v[12:13] op_sel_hi:[1,0]
	v_pk_mul_f32 v[30:31], v[30:31], v[12:13] op_sel_hi:[1,0]
	v_pk_mul_f32 v[28:29], v[28:29], v[12:13] op_sel_hi:[1,0]
	v_pk_mul_f32 v[26:27], v[26:27], v[12:13] op_sel_hi:[1,0]
	v_pk_mul_f32 v[6:7], v[6:7], v[12:13] op_sel_hi:[1,0]
	v_pk_mul_f32 v[4:5], v[4:5], v[12:13] op_sel_hi:[1,0]
	v_pk_mul_f32 v[2:3], v[2:3], v[12:13] op_sel_hi:[1,0]
	v_pk_mul_f32 v[0:1], v[0:1], v[12:13] op_sel_hi:[1,0]
	v_pk_mul_f32 v[24:25], v[24:25], v[12:13] op_sel_hi:[1,0]
	v_pk_mul_f32 v[22:23], v[22:23], v[12:13] op_sel_hi:[1,0]
	v_pk_mul_f32 v[20:21], v[20:21], v[12:13] op_sel_hi:[1,0]
	v_pk_mul_f32 v[18:19], v[18:19], v[12:13] op_sel_hi:[1,0]
	v_pk_mul_f32 v[16:17], v[16:17], v[12:13] op_sel_hi:[1,0]
	v_pk_mul_f32 v[14:15], v[14:15], v[12:13] op_sel_hi:[1,0]
	v_pk_mul_f32 v[10:11], v[10:11], v[12:13] op_sel_hi:[1,0]
	v_pk_mul_f32 v[8:9], v[8:9], v[12:13] op_sel_hi:[1,0]
	s_waitcnt vmcnt(10)
	v_lshlrev_b32_e32 v130, 16, v56
	v_and_b32_e32 v131, 0xffff0000, v56
	v_lshlrev_b32_e32 v132, 16, v57
	v_and_b32_e32 v133, 0xffff0000, v57
	v_pk_fma_f32 v[32:33], v[72:73], v[32:33], v[76:77]
	v_pk_fma_f32 v[30:31], v[74:75], v[30:31], v[78:79]
	global_load_dwordx4 v[72:75], v13, s[22:23] offset:384
	global_load_dwordx4 v[76:79], v13, s[36:37] offset:384
	v_mul_f32_e32 v56, 0xbfb8aa3b, v130
	v_mul_f32_e32 v57, 0xbfb8aa3b, v131
	v_exp_f32_e32 v56, v56
	v_exp_f32_e32 v57, v57
	v_pk_mul_f32 v[32:33], v[32:33], v[130:131]
	v_mul_f32_e32 v130, 0xbfb8aa3b, v132
	v_mul_f32_e32 v131, 0xbfb8aa3b, v133
	v_add_f32_e32 v56, 1.0, v56
	v_add_f32_e32 v57, 1.0, v57
	v_rcp_f32_e32 v56, v56
	v_rcp_f32_e32 v57, v57
	v_exp_f32_e32 v130, v130
	v_exp_f32_e32 v131, v131
	v_pk_mul_f32 v[30:31], v[30:31], v[132:133]
	v_pk_mul_f32 v[32:33], v[56:57], v[32:33]
	v_add_f32_e32 v130, 1.0, v130
	v_add_f32_e32 v131, 1.0, v131
	v_rcp_f32_e32 v130, v130
	v_rcp_f32_e32 v131, v131
	v_cvt_pk_bf16_f32 v56, v32, v33
	s_nop 0
	v_pk_mul_f32 v[30:31], v[130:131], v[30:31]
	s_nop 0
	v_cvt_pk_bf16_f32 v57, v30, v31
	global_store_dwordx2 v[46:47], v[56:57], off
	s_waitcnt vmcnt(11)
; __device__ __forceinline__ unsigned pk2(float lo, float hi) { return pg8::cvt_pk_bf16(lo, hi); }
; __device__ __forceinline__ float bflo(unsigned w) { return __uint_as_float(w << 16); }
; __device__ __forceinline__ float bfhi(unsigned w) { return __uint_as_float(w & 0xffff0000u); }
; __device__ __forceinline__ void ret_unit(LAS unsigned char* lds, int u, const bf16* PROJ, const int* pos, const float* dec_f, const float* dec_b, const bf16* ST,
;                                          const float* gn_w, const float* gn_b, bf16* MIX, int tid, const WsRef& wsr) {
;     ...
;     for (int n = 0; n < 8; ++n) { const int col = h * 128 + n * 16 + 4 * fq;
;         const f32x4 gw = *(const f32x4*)(gn_w + col), gb = *(const f32x4*)(gn_b + col);
;         const u32x2 gg = *(const u32x2*)(PROJ + row * INC + 1536 + col);
;         const f32x4 g = (f32x4){bflo(gg.x), bfhi(gg.x), bflo(gg.y), bfhi(gg.y)};
;         f32x4 y = (o[n] - mu) * rstd * gw + gb;
; #pragma unroll
;         for (int r = 0; r < 4; ++r) y[r] = y[r] * g[r] * __builtin_amdgcn_rcpf(1.f + __expf(-g[r]));
;         u32x2 w; w.x = pk2(y[0], y[1]); w.y = pk2(y[2], y[3]); *(u32x2*)(MIX + row * D + col) = w; }
	v_lshlrev_b32_e32 v130, 16, v58
	v_and_b32_e32 v131, 0xffff0000, v58
	v_lshlrev_b32_e32 v132, 16, v59
	v_and_b32_e32 v133, 0xffff0000, v59
	v_pk_fma_f32 v[28:29], v[80:81], v[28:29], v[84:85]
	v_pk_fma_f32 v[26:27], v[82:83], v[26:27], v[86:87]
	global_load_dwordx4 v[80:83], v13, s[22:23] offset:448
	global_load_dwordx4 v[84:87], v13, s[36:37] offset:448
	v_mul_f32_e32 v58, 0xbfb8aa3b, v130
	v_mul_f32_e32 v59, 0xbfb8aa3b, v131
	v_exp_f32_e32 v58, v58
	v_exp_f32_e32 v59, v59
	v_pk_mul_f32 v[28:29], v[28:29], v[130:131]
	v_mul_f32_e32 v130, 0xbfb8aa3b, v132
	v_mul_f32_e32 v131, 0xbfb8aa3b, v133
	v_add_f32_e32 v58, 1.0, v58
	v_add_f32_e32 v59, 1.0, v59
	v_rcp_f32_e32 v58, v58
	v_rcp_f32_e32 v59, v59
	v_exp_f32_e32 v130, v130
	v_exp_f32_e32 v131, v131
	v_pk_mul_f32 v[26:27], v[26:27], v[132:133]
	v_pk_mul_f32 v[28:29], v[58:59], v[28:29]
	v_add_f32_e32 v130, 1.0, v130
	v_add_f32_e32 v131, 1.0, v131
	v_rcp_f32_e32 v130, v130
	v_rcp_f32_e32 v131, v131
	v_cvt_pk_bf16_f32 v58, v28, v29
	s_nop 0
	v_pk_mul_f32 v[26:27], v[130:131], v[26:27]
	s_nop 0
	v_cvt_pk_bf16_f32 v59, v26, v27
	global_store_dwordx2 v[46:47], v[58:59], off offset:32
	s_waitcnt vmcnt(12)
	v_lshlrev_b32_e32 v130, 16, v60
	v_and_b32_e32 v131, 0xffff0000, v60
	v_lshlrev_b32_e32 v132, 16, v61
	v_and_b32_e32 v133, 0xffff0000, v61
	v_pk_fma_f32 v[6:7], v[88:89], v[6:7], v[92:93]
	v_pk_fma_f32 v[4:5], v[90:91], v[4:5], v[94:95]
	v_mul_f32_e32 v60, 0xbfb8aa3b, v130
	v_mul_f32_e32 v61, 0xbfb8aa3b, v131
	v_exp_f32_e32 v60, v60
	v_exp_f32_e32 v61, v61
	v_pk_mul_f32 v[6:7], v[6:7], v[130:131]
	v_mul_f32_e32 v130, 0xbfb8aa3b, v132
	v_mul_f32_e32 v131, 0xbfb8aa3b, v133
	v_add_f32_e32 v60, 1.0, v60
	v_add_f32_e32 v61, 1.0, v61
	v_rcp_f32_e32 v60, v60
	v_rcp_f32_e32 v61, v61
	v_exp_f32_e32 v130, v130
	v_exp_f32_e32 v131, v131
	v_pk_mul_f32 v[4:5], v[4:5], v[132:133]
	v_pk_mul_f32 v[6:7], v[60:61], v[6:7]
	v_add_f32_e32 v130, 1.0, v130
	v_add_f32_e32 v131, 1.0, v131
	v_rcp_f32_e32 v130, v130
	v_rcp_f32_e32 v131, v131
	v_cvt_pk_bf16_f32 v60, v6, v7
	s_nop 0
	v_pk_mul_f32 v[4:5], v[130:131], v[4:5]
	s_nop 0
	v_cvt_pk_bf16_f32 v61, v4, v5
	global_store_dwordx2 v[46:47], v[60:61], off offset:64
	s_waitcnt vmcnt(11)
	v_lshlrev_b32_e32 v130, 16, v62
	v_and_b32_e32 v131, 0xffff0000, v62
	v_lshlrev_b32_e32 v132, 16, v63
	v_and_b32_e32 v133, 0xffff0000, v63
	v_pk_fma_f32 v[2:3], v[36:37], v[2:3], v[40:41]
	v_pk_fma_f32 v[0:1], v[38:39], v[0:1], v[42:43]
	v_mul_f32_e32 v62, 0xbfb8aa3b, v130
	v_mul_f32_e32 v63, 0xbfb8aa3b, v131
	v_exp_f32_e32 v62, v62
	v_exp_f32_e32 v63, v63
	v_pk_mul_f32 v[2:3], v[2:3], v[130:131]
	v_mul_f32_e32 v130, 0xbfb8aa3b, v132
	v_mul_f32_e32 v131, 0xbfb8aa3b, v133
	v_add_f32_e32 v62, 1.0, v62
	v_add_f32_e32 v63, 1.0, v63
	v_rcp_f32_e32 v62, v62
	v_rcp_f32_e32 v63, v63
	v_exp_f32_e32 v130, v130
	v_exp_f32_e32 v131, v131
	v_pk_mul_f32 v[0:1], v[0:1], v[132:133]
	v_pk_mul_f32 v[2:3], v[62:63], v[2:3]
	v_add_f32_e32 v130, 1.0, v130
	v_add_f32_e32 v131, 1.0, v131
	v_rcp_f32_e32 v130, v130
	v_rcp_f32_e32 v131, v131
	v_cvt_pk_bf16_f32 v62, v2, v3
	s_nop 0
	v_pk_mul_f32 v[0:1], v[130:131], v[0:1]
	s_nop 0
	v_cvt_pk_bf16_f32 v63, v0, v1
	global_store_dwordx2 v[46:47], v[62:63], off offset:96
	s_waitcnt vmcnt(10)
	v_lshlrev_b32_e32 v130, 16, v64
	v_and_b32_e32 v131, 0xffff0000, v64
	v_lshlrev_b32_e32 v132, 16, v65
	v_and_b32_e32 v133, 0xffff0000, v65
	v_pk_fma_f32 v[24:25], v[232:233], v[24:25], v[236:237]
	v_pk_fma_f32 v[22:23], v[234:235], v[22:23], v[238:239]
	v_mul_f32_e32 v64, 0xbfb8aa3b, v130
	v_mul_f32_e32 v65, 0xbfb8aa3b, v131
	v_exp_f32_e32 v64, v64
	v_exp_f32_e32 v65, v65
	v_pk_mul_f32 v[24:25], v[24:25], v[130:131]
	v_mul_f32_e32 v130, 0xbfb8aa3b, v132
	v_mul_f32_e32 v131, 0xbfb8aa3b, v133
	v_add_f32_e32 v64, 1.0, v64
	v_add_f32_e32 v65, 1.0, v65
	v_rcp_f32_e32 v64, v64
	v_rcp_f32_e32 v65, v65
	v_exp_f32_e32 v130, v130
	v_exp_f32_e32 v131, v131
	v_pk_mul_f32 v[22:23], v[22:23], v[132:133]
	v_pk_mul_f32 v[24:25], v[64:65], v[24:25]
	v_add_f32_e32 v130, 1.0, v130
	v_add_f32_e32 v131, 1.0, v131
	v_rcp_f32_e32 v130, v130
	v_rcp_f32_e32 v131, v131
	v_cvt_pk_bf16_f32 v64, v24, v25
	s_nop 0
	v_pk_mul_f32 v[22:23], v[130:131], v[22:23]
	s_nop 0
	v_cvt_pk_bf16_f32 v65, v22, v23
	global_store_dwordx2 v[46:47], v[64:65], off offset:128
	s_waitcnt vmcnt(9)
; __device__ __forceinline__ unsigned pk2(float lo, float hi) { return pg8::cvt_pk_bf16(lo, hi); }
; __device__ __forceinline__ float bflo(unsigned w) { return __uint_as_float(w << 16); }
; __device__ __forceinline__ float bfhi(unsigned w) { return __uint_as_float(w & 0xffff0000u); }
; __device__ __forceinline__ void ret_unit(LAS unsigned char* lds, int u, const bf16* PROJ, const int* pos, const float* dec_f, const float* dec_b, const bf16* ST,
;                                          const float* gn_w, const float* gn_b, bf16* MIX, int tid, const WsRef& wsr) {
;     ...
;     for (int n = 0; n < 8; ++n) { const int col = h * 128 + n * 16 + 4 * fq;
;         const f32x4 gw = *(const f32x4*)(gn_w + col), gb = *(const f32x4*)(gn_b + col);
;         const u32x2 gg = *(const u32x2*)(PROJ + row * INC + 1536 + col);
;         const f32x4 g = (f32x4){bflo(gg.x), bfhi(gg.x), bflo(gg.y), bfhi(gg.y)};
;         f32x4 y = (o[n] - mu) * rstd * gw + gb;
; #pragma unroll
;         for (int r = 0; r < 4; ++r) y[r] = y[r] * g[r] * __builtin_amdgcn_rcpf(1.f + __expf(-g[r]));
;         u32x2 w; w.x = pk2(y[0], y[1]); w.y = pk2(y[2], y[3]); *(u32x2*)(MIX + row * D + col) = w; }
;     __syncthreads();
	v_lshlrev_b32_e32 v130, 16, v66
	v_and_b32_e32 v131, 0xffff0000, v66
	v_lshlrev_b32_e32 v132, 16, v67
	v_and_b32_e32 v133, 0xffff0000, v67
	v_pk_fma_f32 v[20:21], v[240:241], v[20:21], v[248:249]
	v_pk_fma_f32 v[18:19], v[242:243], v[18:19], v[250:251]
	v_mul_f32_e32 v66, 0xbfb8aa3b, v130
	v_mul_f32_e32 v67, 0xbfb8aa3b, v131
	v_exp_f32_e32 v66, v66
	v_exp_f32_e32 v67, v67
	v_pk_mul_f32 v[20:21], v[20:21], v[130:131]
	v_mul_f32_e32 v130, 0xbfb8aa3b, v132
	v_mul_f32_e32 v131, 0xbfb8aa3b, v133
	v_add_f32_e32 v66, 1.0, v66
	v_add_f32_e32 v67, 1.0, v67
	v_rcp_f32_e32 v66, v66
	v_rcp_f32_e32 v67, v67
	v_exp_f32_e32 v130, v130
	v_exp_f32_e32 v131, v131
	v_pk_mul_f32 v[18:19], v[18:19], v[132:133]
	v_pk_mul_f32 v[20:21], v[66:67], v[20:21]
	v_add_f32_e32 v130, 1.0, v130
	v_add_f32_e32 v131, 1.0, v131
	v_rcp_f32_e32 v130, v130
	v_rcp_f32_e32 v131, v131
	v_cvt_pk_bf16_f32 v66, v20, v21
	s_nop 0
	v_pk_mul_f32 v[18:19], v[130:131], v[18:19]
	s_nop 0
	v_cvt_pk_bf16_f32 v67, v18, v19
	global_store_dwordx2 v[46:47], v[66:67], off offset:160
	s_waitcnt vmcnt(8)
	v_lshlrev_b32_e32 v130, 16, v68
	v_and_b32_e32 v131, 0xffff0000, v68
	v_lshlrev_b32_e32 v132, 16, v69
	v_and_b32_e32 v133, 0xffff0000, v69
	v_pk_fma_f32 v[16:17], v[72:73], v[16:17], v[76:77]
	v_pk_fma_f32 v[14:15], v[74:75], v[14:15], v[78:79]
	v_mul_f32_e32 v68, 0xbfb8aa3b, v130
	v_mul_f32_e32 v69, 0xbfb8aa3b, v131
	v_exp_f32_e32 v68, v68
	v_exp_f32_e32 v69, v69
	v_pk_mul_f32 v[16:17], v[16:17], v[130:131]
	v_mul_f32_e32 v130, 0xbfb8aa3b, v132
	v_mul_f32_e32 v131, 0xbfb8aa3b, v133
	v_add_f32_e32 v68, 1.0, v68
	v_add_f32_e32 v69, 1.0, v69
	v_rcp_f32_e32 v68, v68
	v_rcp_f32_e32 v69, v69
	v_exp_f32_e32 v130, v130
	v_exp_f32_e32 v131, v131
	v_pk_mul_f32 v[14:15], v[14:15], v[132:133]
	v_pk_mul_f32 v[16:17], v[68:69], v[16:17]
	v_add_f32_e32 v130, 1.0, v130
	v_add_f32_e32 v131, 1.0, v131
	v_rcp_f32_e32 v130, v130
	v_rcp_f32_e32 v131, v131
	v_cvt_pk_bf16_f32 v68, v16, v17
	s_nop 0
	v_pk_mul_f32 v[14:15], v[130:131], v[14:15]
	s_nop 0
	v_cvt_pk_bf16_f32 v69, v14, v15
	global_store_dwordx2 v[46:47], v[68:69], off offset:192
	s_waitcnt vmcnt(6)
	v_lshlrev_b32_e32 v130, 16, v70
	v_and_b32_e32 v131, 0xffff0000, v70
	v_lshlrev_b32_e32 v132, 16, v71
	v_and_b32_e32 v133, 0xffff0000, v71
	v_pk_fma_f32 v[10:11], v[80:81], v[10:11], v[84:85]
	v_pk_fma_f32 v[8:9], v[82:83], v[8:9], v[86:87]
	v_mul_f32_e32 v70, 0xbfb8aa3b, v130
	v_mul_f32_e32 v71, 0xbfb8aa3b, v131
	v_exp_f32_e32 v70, v70
	v_exp_f32_e32 v71, v71
	v_pk_mul_f32 v[10:11], v[10:11], v[130:131]
	v_mul_f32_e32 v130, 0xbfb8aa3b, v132
	v_mul_f32_e32 v131, 0xbfb8aa3b, v133
	v_add_f32_e32 v70, 1.0, v70
	v_add_f32_e32 v71, 1.0, v71
	v_rcp_f32_e32 v70, v70
	v_rcp_f32_e32 v71, v71
	v_exp_f32_e32 v130, v130
	v_exp_f32_e32 v131, v131
	v_pk_mul_f32 v[8:9], v[8:9], v[132:133]
	v_pk_mul_f32 v[10:11], v[70:71], v[10:11]
	v_add_f32_e32 v130, 1.0, v130
	v_add_f32_e32 v131, 1.0, v131
	v_rcp_f32_e32 v130, v130
	v_rcp_f32_e32 v131, v131
	v_cvt_pk_bf16_f32 v70, v10, v11
	s_nop 0
	v_pk_mul_f32 v[8:9], v[130:131], v[8:9]
	s_nop 0
	v_cvt_pk_bf16_f32 v71, v8, v9
	global_store_dwordx2 v[46:47], v[70:71], off offset:224
	s_barrier
	s_cbranch_scc1 .LBB0_438
	v_readlane_b32 s82, v255, 40
	v_readlane_b32 s4, v255, 38
	v_readlane_b32 s80, v255, 42
	v_readlane_b32 s83, v255, 41
	v_readlane_b32 s5, v255, 39
	v_readlane_b32 s2, v255, 58
	v_readlane_b32 s81, v255, 43
